# attention softmax: dropped self-max canonicalisations of v_max3 results and the pad after the exp block
# speedup vs baseline: 1.0189x; 1.0019x over previous
.LBB0_837:
	s_nop 3
	s_xor_b64 s[12:13], s[54:55], -1
	v_max3_f32 v0, v64, v65, v80
	v_max3_f32 v1, v66, v67, v81
	v_max3_f32 v0, v0, v82, v83
	v_max3_f32 v1, v1, v70, v71
	v_max3_f32 v0, v0, v68, v69
	v_max3_f32 v1, v1, v86, v87
	v_max3_f32 v0, v0, v84, v85
	v_max3_f32 v1, v1, v74, v75
	v_max3_f32 v0, v0, v72, v73
	v_max3_f32 v1, v1, v90, v91
	v_max3_f32 v0, v0, v88, v89
	v_max3_f32 v1, v1, v78, v79
	v_max3_f32 v0, v0, v76, v77
	v_max3_f32 v1, v1, v94, v95
	v_max3_f32 v0, v0, v92, v93
	v_max_f32_e32 v0, v0, v1
	v_mov_b32_e32 v1, v0
	s_nop 1
	v_permlane32_swap_b32_e32 v0, v1
	v_max_f32_e32 v1, v0, v1
	v_cmp_lt_f32_e32 vcc, s14, v1
	s_or_b64 s[16:17], vcc, s[12:13]
	v_cndmask_b32_e64 v0, 0, 1, s[16:17]
	v_cmp_ne_u32_e32 vcc, 0, v0
	s_cbranch_vccz .LBB0_843
	s_and_saveexec_b64 s[16:17], s[12:13]
	s_xor_b64 s[12:13], exec, s[16:17]
	v_cmp_lg_f32_e64 s[54:55], s5, v1
	s_nop 1
	v_cndmask_b32_e64 v48, 0, v1, s[54:55]
	s_or_saveexec_b64 s[12:13], s[12:13]
	v_mov_b32_e32 v0, 1.0
	s_xor_b64 exec, exec, s[12:13]
	v_max_f32_e32 v0, v1, v1
	v_max_f32_e32 v48, 0, v0
	v_exp_f32_e64 v0, -v48
	s_or_b64 s[54:55], s[54:55], exec
	s_or_b64 exec, exec, s[12:13]
	v_add_f32_e32 v181, v181, v48
	v_pk_add_f32 v[64:65], v[64:65], v[48:49] op_sel_hi:[1,0] neg_lo:[0,1] neg_hi:[0,1]
	v_pk_add_f32 v[80:81], v[80:81], v[48:49] op_sel_hi:[1,0] neg_lo:[0,1] neg_hi:[0,1]
	v_pk_add_f32 v[66:67], v[66:67], v[48:49] op_sel_hi:[1,0] neg_lo:[0,1] neg_hi:[0,1]
	v_pk_add_f32 v[82:83], v[82:83], v[48:49] op_sel_hi:[1,0] neg_lo:[0,1] neg_hi:[0,1]
	v_pk_add_f32 v[68:69], v[68:69], v[48:49] op_sel_hi:[1,0] neg_lo:[0,1] neg_hi:[0,1]
	v_pk_add_f32 v[84:85], v[84:85], v[48:49] op_sel_hi:[1,0] neg_lo:[0,1] neg_hi:[0,1]
	v_pk_add_f32 v[70:71], v[70:71], v[48:49] op_sel_hi:[1,0] neg_lo:[0,1] neg_hi:[0,1]
	v_pk_add_f32 v[86:87], v[86:87], v[48:49] op_sel_hi:[1,0] neg_lo:[0,1] neg_hi:[0,1]
	v_pk_add_f32 v[72:73], v[72:73], v[48:49] op_sel_hi:[1,0] neg_lo:[0,1] neg_hi:[0,1]
	v_pk_add_f32 v[88:89], v[88:89], v[48:49] op_sel_hi:[1,0] neg_lo:[0,1] neg_hi:[0,1]
	v_pk_add_f32 v[74:75], v[74:75], v[48:49] op_sel_hi:[1,0] neg_lo:[0,1] neg_hi:[0,1]
	v_pk_add_f32 v[90:91], v[90:91], v[48:49] op_sel_hi:[1,0] neg_lo:[0,1] neg_hi:[0,1]
	v_pk_add_f32 v[76:77], v[76:77], v[48:49] op_sel_hi:[1,0] neg_lo:[0,1] neg_hi:[0,1]
	v_pk_add_f32 v[92:93], v[92:93], v[48:49] op_sel_hi:[1,0] neg_lo:[0,1] neg_hi:[0,1]
	v_pk_add_f32 v[78:79], v[78:79], v[48:49] op_sel_hi:[1,0] neg_lo:[0,1] neg_hi:[0,1]
	v_pk_add_f32 v[94:95], v[94:95], v[48:49] op_sel_hi:[1,0] neg_lo:[0,1] neg_hi:[0,1]
	v_xor_b32_e32 v48, 0x80000000, v181
	v_mul_f32_e32 v180, v180, v0
	v_pk_mul_f32 v[46:47], v[46:47], v[0:1] op_sel_hi:[1,0]
	v_pk_mul_f32 v[44:45], v[44:45], v[0:1] op_sel_hi:[1,0]
	v_pk_mul_f32 v[42:43], v[42:43], v[0:1] op_sel_hi:[1,0]
	v_pk_mul_f32 v[40:41], v[40:41], v[0:1] op_sel_hi:[1,0]
	v_pk_mul_f32 v[38:39], v[38:39], v[0:1] op_sel_hi:[1,0]
	v_pk_mul_f32 v[36:37], v[36:37], v[0:1] op_sel_hi:[1,0]
	v_pk_mul_f32 v[34:35], v[34:35], v[0:1] op_sel_hi:[1,0]
	v_pk_mul_f32 v[32:33], v[32:33], v[0:1] op_sel_hi:[1,0]
	v_pk_mul_f32 v[30:31], v[30:31], v[0:1] op_sel_hi:[1,0]
	v_pk_mul_f32 v[28:29], v[28:29], v[0:1] op_sel_hi:[1,0]
	v_pk_mul_f32 v[26:27], v[26:27], v[0:1] op_sel_hi:[1,0]
	v_pk_mul_f32 v[24:25], v[24:25], v[0:1] op_sel_hi:[1,0]
	v_pk_mul_f32 v[22:23], v[22:23], v[0:1] op_sel_hi:[1,0]
	v_pk_mul_f32 v[20:21], v[20:21], v[0:1] op_sel_hi:[1,0]
	v_pk_mul_f32 v[18:19], v[18:19], v[0:1] op_sel_hi:[1,0]
	v_pk_mul_f32 v[16:17], v[16:17], v[0:1] op_sel_hi:[1,0]
	v_mov_b32_e32 v49, v48
	v_mov_b32_e32 v50, v48
	v_mov_b32_e32 v51, v48
	v_mov_b32_e32 v52, v48
	v_mov_b32_e32 v53, v48
	v_mov_b32_e32 v54, v48
	v_mov_b32_e32 v55, v48
	v_mov_b32_e32 v56, v48
	v_mov_b32_e32 v57, v48
	v_mov_b32_e32 v58, v48
	v_mov_b32_e32 v59, v48
	v_mov_b32_e32 v60, v48
	v_mov_b32_e32 v61, v48
	v_mov_b32_e32 v62, v48
	v_mov_b32_e32 v63, v48
.LBB0_843:
	v_exp_f32_e32 v96, v64
	v_exp_f32_e32 v64, v80
	v_exp_f32_e32 v97, v65
	v_exp_f32_e32 v65, v81
	v_exp_f32_e32 v98, v66
	v_exp_f32_e32 v66, v82
	v_exp_f32_e32 v99, v67
	v_exp_f32_e32 v67, v83
	v_exp_f32_e32 v100, v68
	v_exp_f32_e32 v68, v84
	v_exp_f32_e32 v101, v69
	v_exp_f32_e32 v69, v85
	v_exp_f32_e32 v102, v70
	v_exp_f32_e32 v70, v86
	v_exp_f32_e32 v103, v71
	v_exp_f32_e32 v71, v87
	v_exp_f32_e32 v104, v72
	v_exp_f32_e32 v72, v88
	v_exp_f32_e32 v105, v73
	v_exp_f32_e32 v73, v89
	v_exp_f32_e32 v106, v74
	v_exp_f32_e32 v74, v90
	v_exp_f32_e32 v107, v75
	v_exp_f32_e32 v75, v91
	v_exp_f32_e32 v108, v76
	v_exp_f32_e32 v76, v92
	v_exp_f32_e32 v109, v77
	v_exp_f32_e32 v77, v93
	v_exp_f32_e32 v110, v78
	v_exp_f32_e32 v78, v94
	v_exp_f32_e32 v111, v79
	v_exp_f32_e32 v79, v95
	v_add_f32_e32 v0, v96, v64
	v_add_f32_e32 v1, v97, v65
	v_add_f32_e32 v3, v98, v66
	v_add_f32_e32 v80, v99, v67
	v_cvt_pk_bf16_f32 v81, v98, v99
	v_add_f32_e32 v0, v0, v100
	v_add_f32_e32 v1, v1, v101
	v_add_f32_e32 v3, v3, v102
	v_add_f32_e32 v80, v80, v103
	v_cvt_pk_bf16_f32 v82, v100, v101
	v_add_f32_e32 v0, v0, v68
	v_add_f32_e32 v1, v1, v69
	v_add_f32_e32 v3, v3, v70
	v_add_f32_e32 v80, v80, v71
	v_cvt_pk_bf16_f32 v83, v102, v103
	v_add_f32_e32 v0, v0, v104
	v_add_f32_e32 v1, v1, v105
	v_add_f32_e32 v3, v3, v106
	v_add_f32_e32 v80, v80, v107
	v_cvt_pk_bf16_f32 v84, v104, v105
	v_add_f32_e32 v0, v0, v72
	v_add_f32_e32 v1, v1, v73
	v_add_f32_e32 v3, v3, v74
	v_add_f32_e32 v80, v80, v75
	v_cvt_pk_bf16_f32 v85, v106, v107
	v_add_f32_e32 v0, v0, v108
	v_add_f32_e32 v1, v1, v109
	v_add_f32_e32 v3, v3, v110
	v_add_f32_e32 v80, v80, v111
	v_cvt_pk_bf16_f32 v86, v108, v109
	v_add_f32_e32 v0, v0, v76
	v_add_f32_e32 v1, v1, v77
	v_add_f32_e32 v3, v3, v78
	v_add_f32_e32 v80, v80, v79
	v_cvt_pk_bf16_f32 v87, v110, v111
	v_add_f32_e32 v0, v0, v1
	v_add_f32_e32 v1, v3, v80
	v_cvt_pk_bf16_f32 v80, v96, v97
	v_add_f32_e32 v0, v0, v1
	v_cvt_pk_bf16_f32 v64, v64, v65
	v_add_f32_e32 v180, v180, v0
	v_cvt_pk_bf16_f32 v65, v66, v67
	v_cvt_pk_bf16_f32 v66, v68, v69
	v_cvt_pk_bf16_f32 v67, v70, v71
	v_cvt_pk_bf16_f32 v68, v72, v73
	v_cvt_pk_bf16_f32 v69, v74, v75
	v_cvt_pk_bf16_f32 v70, v76, v77
	v_cvt_pk_bf16_f32 v71, v78, v79
	s_setprio 1
	v_mfma_f32_32x32x16_bf16 v[32:47], v[4:7], v[80:83], v[32:47]
	s_waitcnt lgkmcnt(12)
	v_mfma_f32_32x32x16_bf16 v[16:31], v[8:11], v[80:83], v[16:31]
	s_waitcnt lgkmcnt(10)
	v_mfma_f32_32x32x16_bf16 v[32:47], v[12:15], v[84:87], v[32:47]
	s_waitcnt lgkmcnt(8)
	v_mfma_f32_32x32x16_bf16 v[16:31], v[148:151], v[84:87], v[16:31]
	s_waitcnt lgkmcnt(6)
	v_mfma_f32_32x32x16_bf16 v[32:47], v[152:155], v[64:67], v[32:47]
	s_waitcnt lgkmcnt(4)
	v_mfma_f32_32x32x16_bf16 v[16:31], v[156:159], v[64:67], v[16:31]
	s_waitcnt lgkmcnt(2)
	v_mfma_f32_32x32x16_bf16 v[32:47], v[160:163], v[68:71], v[32:47]
	s_waitcnt lgkmcnt(0)
	v_mfma_f32_32x32x16_bf16 v[16:31], v[164:167], v[68:71], v[16:31]
	s_setprio 0
	s_andn2_b64 vcc, exec, s[56:57]
	s_mov_b64 s[12:13], -1
	s_cbranch_vccz .LBB0_858

.LBB0_850:
	s_nop 9
	s_nop 0
	v_max3_f32 v0, v64, v65, v80
	v_max3_f32 v1, v66, v67, v81
	v_max3_f32 v0, v0, v82, v83
	v_max3_f32 v1, v1, v70, v71
	v_max3_f32 v0, v0, v68, v69
	v_max3_f32 v1, v1, v86, v87
	v_max3_f32 v0, v0, v84, v85
	v_max3_f32 v1, v1, v74, v75
	v_max3_f32 v0, v0, v72, v73
	v_max3_f32 v1, v1, v90, v91
	v_max3_f32 v0, v0, v88, v89
	v_max3_f32 v1, v1, v78, v79
	v_max3_f32 v0, v0, v76, v77
	v_max3_f32 v1, v1, v94, v95
	v_max3_f32 v0, v0, v92, v93
	v_max_f32_e32 v0, v0, v1
	v_mov_b32_e32 v1, v0
	s_nop 1
	v_permlane32_swap_b32_e32 v0, v1
	v_max_f32_e32 v1, v0, v1
	v_cmp_lt_f32_e32 vcc, s14, v1
	s_or_b64 s[16:17], vcc, s[12:13]
	v_cndmask_b32_e64 v0, 0, 1, s[16:17]
	v_cmp_ne_u32_e32 vcc, 0, v0
	s_cbranch_vccz .LBB0_856
	s_and_saveexec_b64 s[16:17], s[12:13]
	s_xor_b64 s[12:13], exec, s[16:17]
	v_cmp_lg_f32_e64 s[54:55], s5, v1
	s_nop 1
	v_cndmask_b32_e64 v48, 0, v1, s[54:55]
	s_or_saveexec_b64 s[12:13], s[12:13]
	v_mov_b32_e32 v0, 1.0
	s_xor_b64 exec, exec, s[12:13]
	v_max_f32_e32 v0, v1, v1
	v_max_f32_e32 v48, 0, v0
	v_exp_f32_e64 v0, -v48
	s_or_b64 s[54:55], s[54:55], exec
	s_or_b64 exec, exec, s[12:13]
	v_add_f32_e32 v181, v181, v48
	v_pk_add_f32 v[64:65], v[64:65], v[48:49] op_sel_hi:[1,0] neg_lo:[0,1] neg_hi:[0,1]
	v_pk_add_f32 v[80:81], v[80:81], v[48:49] op_sel_hi:[1,0] neg_lo:[0,1] neg_hi:[0,1]
	v_pk_add_f32 v[66:67], v[66:67], v[48:49] op_sel_hi:[1,0] neg_lo:[0,1] neg_hi:[0,1]
	v_pk_add_f32 v[82:83], v[82:83], v[48:49] op_sel_hi:[1,0] neg_lo:[0,1] neg_hi:[0,1]
	v_pk_add_f32 v[68:69], v[68:69], v[48:49] op_sel_hi:[1,0] neg_lo:[0,1] neg_hi:[0,1]
	v_pk_add_f32 v[84:85], v[84:85], v[48:49] op_sel_hi:[1,0] neg_lo:[0,1] neg_hi:[0,1]
	v_pk_add_f32 v[70:71], v[70:71], v[48:49] op_sel_hi:[1,0] neg_lo:[0,1] neg_hi:[0,1]
	v_pk_add_f32 v[86:87], v[86:87], v[48:49] op_sel_hi:[1,0] neg_lo:[0,1] neg_hi:[0,1]
	v_pk_add_f32 v[72:73], v[72:73], v[48:49] op_sel_hi:[1,0] neg_lo:[0,1] neg_hi:[0,1]
	v_pk_add_f32 v[88:89], v[88:89], v[48:49] op_sel_hi:[1,0] neg_lo:[0,1] neg_hi:[0,1]
	v_pk_add_f32 v[74:75], v[74:75], v[48:49] op_sel_hi:[1,0] neg_lo:[0,1] neg_hi:[0,1]
	v_pk_add_f32 v[90:91], v[90:91], v[48:49] op_sel_hi:[1,0] neg_lo:[0,1] neg_hi:[0,1]
	v_pk_add_f32 v[76:77], v[76:77], v[48:49] op_sel_hi:[1,0] neg_lo:[0,1] neg_hi:[0,1]
	v_pk_add_f32 v[92:93], v[92:93], v[48:49] op_sel_hi:[1,0] neg_lo:[0,1] neg_hi:[0,1]
	v_pk_add_f32 v[78:79], v[78:79], v[48:49] op_sel_hi:[1,0] neg_lo:[0,1] neg_hi:[0,1]
	v_pk_add_f32 v[94:95], v[94:95], v[48:49] op_sel_hi:[1,0] neg_lo:[0,1] neg_hi:[0,1]
	v_xor_b32_e32 v48, 0x80000000, v181
	v_mul_f32_e32 v180, v180, v0
	v_pk_mul_f32 v[46:47], v[46:47], v[0:1] op_sel_hi:[1,0]
	v_pk_mul_f32 v[44:45], v[44:45], v[0:1] op_sel_hi:[1,0]
	v_pk_mul_f32 v[42:43], v[42:43], v[0:1] op_sel_hi:[1,0]
	v_pk_mul_f32 v[40:41], v[40:41], v[0:1] op_sel_hi:[1,0]
	v_pk_mul_f32 v[38:39], v[38:39], v[0:1] op_sel_hi:[1,0]
	v_pk_mul_f32 v[36:37], v[36:37], v[0:1] op_sel_hi:[1,0]
	v_pk_mul_f32 v[34:35], v[34:35], v[0:1] op_sel_hi:[1,0]
	v_pk_mul_f32 v[32:33], v[32:33], v[0:1] op_sel_hi:[1,0]
	v_pk_mul_f32 v[30:31], v[30:31], v[0:1] op_sel_hi:[1,0]
	v_pk_mul_f32 v[28:29], v[28:29], v[0:1] op_sel_hi:[1,0]
	v_pk_mul_f32 v[26:27], v[26:27], v[0:1] op_sel_hi:[1,0]
	v_pk_mul_f32 v[24:25], v[24:25], v[0:1] op_sel_hi:[1,0]
	v_pk_mul_f32 v[22:23], v[22:23], v[0:1] op_sel_hi:[1,0]
	v_pk_mul_f32 v[20:21], v[20:21], v[0:1] op_sel_hi:[1,0]
	v_pk_mul_f32 v[18:19], v[18:19], v[0:1] op_sel_hi:[1,0]
	v_pk_mul_f32 v[16:17], v[16:17], v[0:1] op_sel_hi:[1,0]
	v_mov_b32_e32 v49, v48
	v_mov_b32_e32 v50, v48
	v_mov_b32_e32 v51, v48
	v_mov_b32_e32 v52, v48
	v_mov_b32_e32 v53, v48
	v_mov_b32_e32 v54, v48
	v_mov_b32_e32 v55, v48
	v_mov_b32_e32 v56, v48
	v_mov_b32_e32 v57, v48
	v_mov_b32_e32 v58, v48
	v_mov_b32_e32 v59, v48
	v_mov_b32_e32 v60, v48
	v_mov_b32_e32 v61, v48
	v_mov_b32_e32 v62, v48
	v_mov_b32_e32 v63, v48
.LBB0_856:
	v_exp_f32_e32 v96, v64
	v_exp_f32_e32 v64, v80
	v_exp_f32_e32 v97, v65
	v_exp_f32_e32 v65, v81
	v_exp_f32_e32 v98, v66
	v_exp_f32_e32 v66, v82
	v_exp_f32_e32 v99, v67
	v_exp_f32_e32 v67, v83
	v_exp_f32_e32 v100, v68
	v_exp_f32_e32 v68, v84
	v_exp_f32_e32 v101, v69
	v_exp_f32_e32 v69, v85
	v_exp_f32_e32 v102, v70
	v_exp_f32_e32 v70, v86
	v_exp_f32_e32 v103, v71
	v_exp_f32_e32 v71, v87
	v_exp_f32_e32 v104, v72
	v_exp_f32_e32 v72, v88
	v_exp_f32_e32 v105, v73
	v_exp_f32_e32 v73, v89
	v_exp_f32_e32 v106, v74
	v_exp_f32_e32 v74, v90
	v_exp_f32_e32 v107, v75
	v_exp_f32_e32 v75, v91
	v_exp_f32_e32 v108, v76
	v_exp_f32_e32 v76, v92
	v_exp_f32_e32 v109, v77
	v_exp_f32_e32 v77, v93
	v_exp_f32_e32 v110, v78
	v_exp_f32_e32 v78, v94
	v_exp_f32_e32 v111, v79
	v_exp_f32_e32 v79, v95
	v_add_f32_e32 v0, v96, v64
	v_add_f32_e32 v1, v97, v65
	v_add_f32_e32 v3, v98, v66
	v_add_f32_e32 v80, v99, v67
	v_cvt_pk_bf16_f32 v81, v98, v99
	v_add_f32_e32 v0, v0, v100
	v_add_f32_e32 v1, v1, v101
	v_add_f32_e32 v3, v3, v102
	v_add_f32_e32 v80, v80, v103
	v_cvt_pk_bf16_f32 v82, v100, v101
	v_add_f32_e32 v0, v0, v68
	v_add_f32_e32 v1, v1, v69
	v_add_f32_e32 v3, v3, v70
	v_add_f32_e32 v80, v80, v71
	v_cvt_pk_bf16_f32 v83, v102, v103
	v_add_f32_e32 v0, v0, v104
	v_add_f32_e32 v1, v1, v105
	v_add_f32_e32 v3, v3, v106
	v_add_f32_e32 v80, v80, v107
	v_cvt_pk_bf16_f32 v84, v104, v105
	v_add_f32_e32 v0, v0, v72
	v_add_f32_e32 v1, v1, v73
	v_add_f32_e32 v3, v3, v74
	v_add_f32_e32 v80, v80, v75
	v_cvt_pk_bf16_f32 v85, v106, v107
	v_add_f32_e32 v0, v0, v108
	v_add_f32_e32 v1, v1, v109
	v_add_f32_e32 v3, v3, v110
	v_add_f32_e32 v80, v80, v111
	v_cvt_pk_bf16_f32 v86, v108, v109
	v_add_f32_e32 v0, v0, v76
	v_add_f32_e32 v1, v1, v77
	v_add_f32_e32 v3, v3, v78
	v_add_f32_e32 v80, v80, v79
	v_cvt_pk_bf16_f32 v87, v110, v111
	v_add_f32_e32 v0, v0, v1
	v_add_f32_e32 v1, v3, v80
	v_cvt_pk_bf16_f32 v80, v96, v97
	v_add_f32_e32 v0, v0, v1
	v_cvt_pk_bf16_f32 v64, v64, v65
	v_add_f32_e32 v180, v180, v0
	v_cvt_pk_bf16_f32 v65, v66, v67
	v_cvt_pk_bf16_f32 v66, v68, v69
	v_cvt_pk_bf16_f32 v67, v70, v71
	v_cvt_pk_bf16_f32 v68, v72, v73
	v_cvt_pk_bf16_f32 v69, v74, v75
	v_cvt_pk_bf16_f32 v70, v76, v77
	v_cvt_pk_bf16_f32 v71, v78, v79
	s_setprio 1
	v_mfma_f32_32x32x16_bf16 v[32:47], v[4:7], v[80:83], v[32:47]
	s_waitcnt lgkmcnt(12)
	v_mfma_f32_32x32x16_bf16 v[16:31], v[8:11], v[80:83], v[16:31]
	s_waitcnt lgkmcnt(10)
	v_mfma_f32_32x32x16_bf16 v[32:47], v[12:15], v[84:87], v[32:47]
	s_waitcnt lgkmcnt(8)
	v_mfma_f32_32x32x16_bf16 v[16:31], v[148:151], v[84:87], v[16:31]
	s_waitcnt lgkmcnt(6)
	v_mfma_f32_32x32x16_bf16 v[32:47], v[152:155], v[64:67], v[32:47]
	s_waitcnt lgkmcnt(4)
	v_mfma_f32_32x32x16_bf16 v[16:31], v[156:159], v[64:67], v[16:31]
	s_waitcnt lgkmcnt(2)
	v_mfma_f32_32x32x16_bf16 v[32:47], v[160:163], v[68:71], v[32:47]
	s_waitcnt lgkmcnt(0)
	v_mfma_f32_32x32x16_bf16 v[16:31], v[164:167], v[68:71], v[16:31]
	s_setprio 0
	s_add_i32 s2, s63, 0xffffff81
	s_cmp_gt_i32 s2, s61
	s_cbranch_scc0 .LBB0_833

.LBB0_878:
	s_nop 8
	s_xor_b64 s[16:17], s[52:53], -1
	v_max3_f32 v0, v80, v81, v96
	v_max3_f32 v1, v82, v83, v97
	v_max3_f32 v0, v0, v98, v99
	v_max3_f32 v1, v1, v86, v87
	v_max3_f32 v0, v0, v84, v85
	v_max3_f32 v1, v1, v102, v103
	v_max3_f32 v0, v0, v100, v101
	v_max3_f32 v1, v1, v90, v91
	v_max3_f32 v0, v0, v88, v89
	v_max3_f32 v1, v1, v106, v107
	v_max3_f32 v0, v0, v104, v105
	v_max3_f32 v1, v1, v94, v95
	v_max3_f32 v0, v0, v92, v93
	v_max3_f32 v1, v1, v110, v111
	v_max3_f32 v0, v0, v108, v109
	v_max_f32_e32 v0, v0, v1
	v_mov_b32_e32 v1, v0
	s_nop 1
	v_permlane32_swap_b32_e32 v0, v1
	v_max_f32_e32 v1, v0, v1
	v_cmp_lt_f32_e32 vcc, s14, v1
	s_or_b64 s[18:19], vcc, s[16:17]
	v_cndmask_b32_e64 v0, 0, 1, s[18:19]
	v_cmp_ne_u32_e32 vcc, 0, v0
	s_cbranch_vccz .LBB0_884
	s_and_saveexec_b64 s[18:19], s[16:17]
	s_xor_b64 s[16:17], exec, s[18:19]
	v_cmp_lg_f32_e64 s[52:53], s5, v1
	s_nop 1
	v_cndmask_b32_e64 v48, 0, v1, s[52:53]
	s_or_saveexec_b64 s[16:17], s[16:17]
	v_mov_b32_e32 v0, 1.0
	s_xor_b64 exec, exec, s[16:17]
	v_max_f32_e32 v0, v1, v1
	v_max_f32_e32 v48, 0, v0
	v_exp_f32_e64 v0, -v48
	s_or_b64 s[52:53], s[52:53], exec
	s_or_b64 exec, exec, s[16:17]
	v_add_f32_e32 v219, v219, v48
	v_pk_add_f32 v[80:81], v[80:81], v[48:49] op_sel_hi:[1,0] neg_lo:[0,1] neg_hi:[0,1]
	v_pk_add_f32 v[96:97], v[96:97], v[48:49] op_sel_hi:[1,0] neg_lo:[0,1] neg_hi:[0,1]
	v_pk_add_f32 v[82:83], v[82:83], v[48:49] op_sel_hi:[1,0] neg_lo:[0,1] neg_hi:[0,1]
	v_pk_add_f32 v[98:99], v[98:99], v[48:49] op_sel_hi:[1,0] neg_lo:[0,1] neg_hi:[0,1]
	v_pk_add_f32 v[84:85], v[84:85], v[48:49] op_sel_hi:[1,0] neg_lo:[0,1] neg_hi:[0,1]
	v_pk_add_f32 v[100:101], v[100:101], v[48:49] op_sel_hi:[1,0] neg_lo:[0,1] neg_hi:[0,1]
	v_pk_add_f32 v[86:87], v[86:87], v[48:49] op_sel_hi:[1,0] neg_lo:[0,1] neg_hi:[0,1]
	v_pk_add_f32 v[102:103], v[102:103], v[48:49] op_sel_hi:[1,0] neg_lo:[0,1] neg_hi:[0,1]
	v_pk_add_f32 v[88:89], v[88:89], v[48:49] op_sel_hi:[1,0] neg_lo:[0,1] neg_hi:[0,1]
	v_pk_add_f32 v[104:105], v[104:105], v[48:49] op_sel_hi:[1,0] neg_lo:[0,1] neg_hi:[0,1]
	v_pk_add_f32 v[90:91], v[90:91], v[48:49] op_sel_hi:[1,0] neg_lo:[0,1] neg_hi:[0,1]
	v_pk_add_f32 v[106:107], v[106:107], v[48:49] op_sel_hi:[1,0] neg_lo:[0,1] neg_hi:[0,1]
	v_pk_add_f32 v[92:93], v[92:93], v[48:49] op_sel_hi:[1,0] neg_lo:[0,1] neg_hi:[0,1]
	v_pk_add_f32 v[108:109], v[108:109], v[48:49] op_sel_hi:[1,0] neg_lo:[0,1] neg_hi:[0,1]
	v_pk_add_f32 v[94:95], v[94:95], v[48:49] op_sel_hi:[1,0] neg_lo:[0,1] neg_hi:[0,1]
	v_pk_add_f32 v[110:111], v[110:111], v[48:49] op_sel_hi:[1,0] neg_lo:[0,1] neg_hi:[0,1]
	v_xor_b32_e32 v48, 0x80000000, v219
	v_mul_f32_e32 v209, v209, v0
	v_pk_mul_f32 v[46:47], v[46:47], v[0:1] op_sel_hi:[1,0]
	v_pk_mul_f32 v[44:45], v[44:45], v[0:1] op_sel_hi:[1,0]
	v_pk_mul_f32 v[42:43], v[42:43], v[0:1] op_sel_hi:[1,0]
	v_pk_mul_f32 v[40:41], v[40:41], v[0:1] op_sel_hi:[1,0]
	v_pk_mul_f32 v[38:39], v[38:39], v[0:1] op_sel_hi:[1,0]
	v_pk_mul_f32 v[36:37], v[36:37], v[0:1] op_sel_hi:[1,0]
	v_pk_mul_f32 v[34:35], v[34:35], v[0:1] op_sel_hi:[1,0]
	v_pk_mul_f32 v[32:33], v[32:33], v[0:1] op_sel_hi:[1,0]
	v_pk_mul_f32 v[30:31], v[30:31], v[0:1] op_sel_hi:[1,0]
	v_pk_mul_f32 v[28:29], v[28:29], v[0:1] op_sel_hi:[1,0]
	v_pk_mul_f32 v[26:27], v[26:27], v[0:1] op_sel_hi:[1,0]
	v_pk_mul_f32 v[24:25], v[24:25], v[0:1] op_sel_hi:[1,0]
	v_pk_mul_f32 v[22:23], v[22:23], v[0:1] op_sel_hi:[1,0]
	v_pk_mul_f32 v[20:21], v[20:21], v[0:1] op_sel_hi:[1,0]
	v_pk_mul_f32 v[18:19], v[18:19], v[0:1] op_sel_hi:[1,0]
	v_pk_mul_f32 v[16:17], v[16:17], v[0:1] op_sel_hi:[1,0]
	v_mov_b32_e32 v49, v48
	v_mov_b32_e32 v50, v48
	v_mov_b32_e32 v51, v48
	v_mov_b32_e32 v52, v48
	v_mov_b32_e32 v53, v48
	v_mov_b32_e32 v54, v48
	v_mov_b32_e32 v55, v48
	v_mov_b32_e32 v56, v48
	v_mov_b32_e32 v57, v48
	v_mov_b32_e32 v58, v48
	v_mov_b32_e32 v59, v48
	v_mov_b32_e32 v60, v48
	v_mov_b32_e32 v61, v48
	v_mov_b32_e32 v62, v48
	v_mov_b32_e32 v63, v48
	v_mov_b32_e32 v79, v48
	v_mov_b32_e32 v78, v48
	v_mov_b32_e32 v77, v48
	v_mov_b32_e32 v76, v48
	v_mov_b32_e32 v75, v48
	v_mov_b32_e32 v74, v48
	v_mov_b32_e32 v73, v48
	v_mov_b32_e32 v72, v48
	v_mov_b32_e32 v71, v48
	v_mov_b32_e32 v70, v48
	v_mov_b32_e32 v69, v48
	v_mov_b32_e32 v68, v48
	v_mov_b32_e32 v67, v48
	v_mov_b32_e32 v66, v48
	v_mov_b32_e32 v65, v48
	v_mov_b32_e32 v64, v48
	s_branch .LBB0_885

.LBB0_885:
	v_exp_f32_e32 v112, v80
	v_exp_f32_e32 v80, v96
	v_exp_f32_e32 v113, v81
	v_exp_f32_e32 v81, v97
	v_exp_f32_e32 v114, v82
	v_exp_f32_e32 v82, v98
	v_exp_f32_e32 v115, v83
	v_exp_f32_e32 v83, v99
	v_exp_f32_e32 v116, v84
	v_exp_f32_e32 v84, v100
	v_exp_f32_e32 v117, v85
	v_exp_f32_e32 v85, v101
	v_exp_f32_e32 v118, v86
	v_exp_f32_e32 v86, v102
	v_exp_f32_e32 v119, v87
	v_exp_f32_e32 v87, v103
	v_exp_f32_e32 v120, v88
	v_exp_f32_e32 v88, v104
	v_exp_f32_e32 v121, v89
	v_exp_f32_e32 v89, v105
	v_exp_f32_e32 v122, v90
	v_exp_f32_e32 v90, v106
	v_exp_f32_e32 v123, v91
	v_exp_f32_e32 v91, v107
	v_exp_f32_e32 v124, v92
	v_exp_f32_e32 v92, v108
	v_exp_f32_e32 v125, v93
	v_exp_f32_e32 v93, v109
	v_exp_f32_e32 v126, v94
	v_exp_f32_e32 v94, v110
	v_exp_f32_e32 v127, v95
	v_exp_f32_e32 v95, v111
	s_mov_b64 s[16:17], -1
	v_add_f32_e32 v0, v112, v80
	v_add_f32_e32 v1, v113, v81
	v_add_f32_e32 v3, v114, v82
	v_add_f32_e32 v96, v115, v83
	v_cvt_pk_bf16_f32 v97, v114, v115
	v_add_f32_e32 v0, v0, v116
	v_add_f32_e32 v1, v1, v117
	v_add_f32_e32 v3, v3, v118
	v_add_f32_e32 v96, v96, v119
	v_cvt_pk_bf16_f32 v98, v116, v117
	v_add_f32_e32 v0, v0, v84
	v_add_f32_e32 v1, v1, v85
	v_add_f32_e32 v3, v3, v86
	v_add_f32_e32 v96, v96, v87
	v_cvt_pk_bf16_f32 v99, v118, v119
	v_add_f32_e32 v0, v0, v120
	v_add_f32_e32 v1, v1, v121
	v_add_f32_e32 v3, v3, v122
	v_add_f32_e32 v96, v96, v123
	v_cvt_pk_bf16_f32 v100, v120, v121
	v_add_f32_e32 v0, v0, v88
	v_add_f32_e32 v1, v1, v89
	v_add_f32_e32 v3, v3, v90
	v_add_f32_e32 v96, v96, v91
	v_cvt_pk_bf16_f32 v101, v122, v123
	v_add_f32_e32 v0, v0, v124
	v_add_f32_e32 v1, v1, v125
	v_add_f32_e32 v3, v3, v126
	v_add_f32_e32 v96, v96, v127
	v_cvt_pk_bf16_f32 v102, v124, v125
	v_add_f32_e32 v0, v0, v92
	v_add_f32_e32 v1, v1, v93
	v_add_f32_e32 v3, v3, v94
	v_add_f32_e32 v96, v96, v95
	v_cvt_pk_bf16_f32 v103, v126, v127
	v_add_f32_e32 v0, v0, v1
	v_add_f32_e32 v1, v3, v96
	v_cvt_pk_bf16_f32 v96, v112, v113
	v_add_f32_e32 v0, v0, v1
	v_cvt_pk_bf16_f32 v80, v80, v81
	v_add_f32_e32 v209, v209, v0
	v_cvt_pk_bf16_f32 v81, v82, v83
	v_cvt_pk_bf16_f32 v82, v84, v85
	v_cvt_pk_bf16_f32 v83, v86, v87
	v_cvt_pk_bf16_f32 v84, v88, v89
	v_cvt_pk_bf16_f32 v85, v90, v91
	v_cvt_pk_bf16_f32 v86, v92, v93
	v_cvt_pk_bf16_f32 v87, v94, v95
	s_setprio 1
	v_mfma_f32_32x32x16_bf16 v[32:47], v[4:7], v[96:99], v[32:47]
	s_waitcnt lgkmcnt(12)
	v_mfma_f32_32x32x16_bf16 v[16:31], v[8:11], v[96:99], v[16:31]
	s_waitcnt lgkmcnt(10)
	v_mfma_f32_32x32x16_bf16 v[32:47], v[12:15], v[100:103], v[32:47]
	s_waitcnt lgkmcnt(8)
	v_mfma_f32_32x32x16_bf16 v[16:31], v[164:167], v[100:103], v[16:31]
	s_waitcnt lgkmcnt(6)
	v_mfma_f32_32x32x16_bf16 v[32:47], v[168:171], v[80:83], v[32:47]
	s_waitcnt lgkmcnt(4)
	v_mfma_f32_32x32x16_bf16 v[16:31], v[172:175], v[80:83], v[16:31]
	s_waitcnt lgkmcnt(2)
	v_mfma_f32_32x32x16_bf16 v[32:47], v[176:179], v[84:87], v[32:47]
	s_waitcnt lgkmcnt(0)
	v_mfma_f32_32x32x16_bf16 v[16:31], v[180:183], v[84:87], v[16:31]
	s_setprio 0
	s_cmp_lt_i32 s56, 0
	s_cbranch_scc1 .LBB0_900
	s_lshl_b64 s[16:17], 1, s69
	s_andn2_b64 s[58:59], s[12:13], s[16:17]
	s_ff1_i32_b64 s2, s[58:59]
	s_cmp_lg_u64 s[58:59], 0
	s_cselect_b32 s0, s2, -1
	s_cmp_lt_i32 s0, 0
	s_waitcnt vmcnt(1)
	ds_write_b128 v192, v[156:159] offset:9216
	s_waitcnt vmcnt(0)
	ds_write_b128 v194, v[160:163] offset:30720
	s_waitcnt lgkmcnt(0)
	s_barrier
	s_cbranch_scc1 .LBB0_888
	s_lshl_b64 s[12:13], s[0:1], 14
	v_lshl_add_u64 v[0:1], v[214:215], 0, s[12:13]
	v_lshl_add_u64 v[4:5], v[216:217], 0, s[12:13]
	global_load_dwordx4 v[156:159], v[0:1], off
	global_load_dwordx4 v[160:163], v[4:5], off

.LBB0_892:
	s_nop 8
	s_xor_b64 s[12:13], s[52:53], -1
	v_max3_f32 v0, v80, v81, v96
	v_max3_f32 v1, v82, v83, v97
	v_max3_f32 v0, v0, v98, v99
	v_max3_f32 v1, v1, v86, v87
	v_max3_f32 v0, v0, v84, v85
	v_max3_f32 v1, v1, v102, v103
	v_max3_f32 v0, v0, v100, v101
	v_max3_f32 v1, v1, v90, v91
	v_max3_f32 v0, v0, v88, v89
	v_max3_f32 v1, v1, v106, v107
	v_max3_f32 v0, v0, v104, v105
	v_max3_f32 v1, v1, v94, v95
	v_max3_f32 v0, v0, v92, v93
	v_max3_f32 v1, v1, v110, v111
	v_max3_f32 v0, v0, v108, v109
	v_max_f32_e32 v0, v0, v1
	v_mov_b32_e32 v1, v0
	s_nop 1
	v_permlane32_swap_b32_e32 v0, v1
	v_max_f32_e32 v1, v0, v1
	v_cmp_lt_f32_e32 vcc, s14, v1
	s_or_b64 s[16:17], vcc, s[12:13]
	v_cndmask_b32_e64 v0, 0, 1, s[16:17]
	v_cmp_ne_u32_e32 vcc, 0, v0
	s_cbranch_vccz .LBB0_898
	s_and_saveexec_b64 s[16:17], s[12:13]
	s_xor_b64 s[12:13], exec, s[16:17]
	v_cmp_lg_f32_e64 s[52:53], s5, v1
	s_nop 1
	v_cndmask_b32_e64 v48, 0, v1, s[52:53]
	s_or_saveexec_b64 s[12:13], s[12:13]
	v_mov_b32_e32 v0, 1.0
	s_xor_b64 exec, exec, s[12:13]
	v_max_f32_e32 v0, v1, v1
	v_max_f32_e32 v48, 0, v0
	v_exp_f32_e64 v0, -v48
	s_or_b64 s[52:53], s[52:53], exec
	s_or_b64 exec, exec, s[12:13]
	v_add_f32_e32 v219, v219, v48
	v_pk_add_f32 v[80:81], v[80:81], v[48:49] op_sel_hi:[1,0] neg_lo:[0,1] neg_hi:[0,1]
	v_pk_add_f32 v[96:97], v[96:97], v[48:49] op_sel_hi:[1,0] neg_lo:[0,1] neg_hi:[0,1]
	v_pk_add_f32 v[82:83], v[82:83], v[48:49] op_sel_hi:[1,0] neg_lo:[0,1] neg_hi:[0,1]
	v_pk_add_f32 v[98:99], v[98:99], v[48:49] op_sel_hi:[1,0] neg_lo:[0,1] neg_hi:[0,1]
	v_pk_add_f32 v[84:85], v[84:85], v[48:49] op_sel_hi:[1,0] neg_lo:[0,1] neg_hi:[0,1]
	v_pk_add_f32 v[100:101], v[100:101], v[48:49] op_sel_hi:[1,0] neg_lo:[0,1] neg_hi:[0,1]
	v_pk_add_f32 v[86:87], v[86:87], v[48:49] op_sel_hi:[1,0] neg_lo:[0,1] neg_hi:[0,1]
	v_pk_add_f32 v[102:103], v[102:103], v[48:49] op_sel_hi:[1,0] neg_lo:[0,1] neg_hi:[0,1]
	v_pk_add_f32 v[88:89], v[88:89], v[48:49] op_sel_hi:[1,0] neg_lo:[0,1] neg_hi:[0,1]
	v_pk_add_f32 v[104:105], v[104:105], v[48:49] op_sel_hi:[1,0] neg_lo:[0,1] neg_hi:[0,1]
	v_pk_add_f32 v[90:91], v[90:91], v[48:49] op_sel_hi:[1,0] neg_lo:[0,1] neg_hi:[0,1]
	v_pk_add_f32 v[106:107], v[106:107], v[48:49] op_sel_hi:[1,0] neg_lo:[0,1] neg_hi:[0,1]
	v_pk_add_f32 v[92:93], v[92:93], v[48:49] op_sel_hi:[1,0] neg_lo:[0,1] neg_hi:[0,1]
	v_pk_add_f32 v[108:109], v[108:109], v[48:49] op_sel_hi:[1,0] neg_lo:[0,1] neg_hi:[0,1]
	v_pk_add_f32 v[94:95], v[94:95], v[48:49] op_sel_hi:[1,0] neg_lo:[0,1] neg_hi:[0,1]
	v_pk_add_f32 v[110:111], v[110:111], v[48:49] op_sel_hi:[1,0] neg_lo:[0,1] neg_hi:[0,1]
	v_xor_b32_e32 v48, 0x80000000, v219
	v_mul_f32_e32 v209, v209, v0
	v_pk_mul_f32 v[46:47], v[46:47], v[0:1] op_sel_hi:[1,0]
	v_pk_mul_f32 v[44:45], v[44:45], v[0:1] op_sel_hi:[1,0]
	v_pk_mul_f32 v[42:43], v[42:43], v[0:1] op_sel_hi:[1,0]
	v_pk_mul_f32 v[40:41], v[40:41], v[0:1] op_sel_hi:[1,0]
	v_pk_mul_f32 v[38:39], v[38:39], v[0:1] op_sel_hi:[1,0]
	v_pk_mul_f32 v[36:37], v[36:37], v[0:1] op_sel_hi:[1,0]
	v_pk_mul_f32 v[34:35], v[34:35], v[0:1] op_sel_hi:[1,0]
	v_pk_mul_f32 v[32:33], v[32:33], v[0:1] op_sel_hi:[1,0]
	v_pk_mul_f32 v[30:31], v[30:31], v[0:1] op_sel_hi:[1,0]
	v_pk_mul_f32 v[28:29], v[28:29], v[0:1] op_sel_hi:[1,0]
	v_pk_mul_f32 v[26:27], v[26:27], v[0:1] op_sel_hi:[1,0]
	v_pk_mul_f32 v[24:25], v[24:25], v[0:1] op_sel_hi:[1,0]
	v_pk_mul_f32 v[22:23], v[22:23], v[0:1] op_sel_hi:[1,0]
	v_pk_mul_f32 v[20:21], v[20:21], v[0:1] op_sel_hi:[1,0]
	v_pk_mul_f32 v[18:19], v[18:19], v[0:1] op_sel_hi:[1,0]
	v_pk_mul_f32 v[16:17], v[16:17], v[0:1] op_sel_hi:[1,0]
	v_mov_b32_e32 v49, v48
	v_mov_b32_e32 v50, v48
	v_mov_b32_e32 v51, v48
	v_mov_b32_e32 v52, v48
	v_mov_b32_e32 v53, v48
	v_mov_b32_e32 v54, v48
	v_mov_b32_e32 v55, v48
	v_mov_b32_e32 v56, v48
	v_mov_b32_e32 v57, v48
	v_mov_b32_e32 v58, v48
	v_mov_b32_e32 v59, v48
	v_mov_b32_e32 v60, v48
	v_mov_b32_e32 v61, v48
	v_mov_b32_e32 v62, v48
	v_mov_b32_e32 v63, v48
	v_mov_b32_e32 v79, v48
	v_mov_b32_e32 v78, v48
	v_mov_b32_e32 v77, v48
	v_mov_b32_e32 v76, v48
	v_mov_b32_e32 v75, v48
	v_mov_b32_e32 v74, v48
	v_mov_b32_e32 v73, v48
	v_mov_b32_e32 v72, v48
	v_mov_b32_e32 v71, v48
	v_mov_b32_e32 v70, v48
	v_mov_b32_e32 v69, v48
	v_mov_b32_e32 v68, v48
	v_mov_b32_e32 v67, v48
	v_mov_b32_e32 v66, v48
	v_mov_b32_e32 v65, v48
	v_mov_b32_e32 v64, v48
.LBB0_898:
	v_exp_f32_e32 v112, v80
	v_exp_f32_e32 v80, v96
	v_exp_f32_e32 v113, v81
	v_exp_f32_e32 v81, v97
	v_exp_f32_e32 v114, v82
	v_exp_f32_e32 v82, v98
	v_exp_f32_e32 v115, v83
	v_exp_f32_e32 v83, v99
	v_exp_f32_e32 v116, v84
	v_exp_f32_e32 v84, v100
	v_exp_f32_e32 v117, v85
	v_exp_f32_e32 v85, v101
	v_exp_f32_e32 v118, v86
	v_exp_f32_e32 v86, v102
	v_exp_f32_e32 v119, v87
	v_exp_f32_e32 v87, v103
	v_exp_f32_e32 v120, v88
	v_exp_f32_e32 v88, v104
	v_exp_f32_e32 v121, v89
	v_exp_f32_e32 v89, v105
	v_exp_f32_e32 v122, v90
	v_exp_f32_e32 v90, v106
	v_exp_f32_e32 v123, v91
	v_exp_f32_e32 v91, v107
	v_exp_f32_e32 v124, v92
	v_exp_f32_e32 v92, v108
	v_exp_f32_e32 v125, v93
	v_exp_f32_e32 v93, v109
	v_exp_f32_e32 v126, v94
	v_exp_f32_e32 v94, v110
	v_exp_f32_e32 v127, v95
	v_exp_f32_e32 v95, v111
	v_add_f32_e32 v0, v112, v80
	v_add_f32_e32 v1, v113, v81
	v_add_f32_e32 v96, v115, v83
	v_add_f32_e32 v3, v114, v82
	v_cvt_pk_bf16_f32 v97, v114, v115
	v_add_f32_e32 v0, v0, v116
	v_add_f32_e32 v1, v1, v117
	v_add_f32_e32 v96, v96, v119
	v_add_f32_e32 v3, v3, v118
	v_cvt_pk_bf16_f32 v98, v116, v117
	v_add_f32_e32 v0, v0, v84
	v_add_f32_e32 v1, v1, v85
	v_add_f32_e32 v96, v96, v87
	v_add_f32_e32 v3, v3, v86
	v_cvt_pk_bf16_f32 v99, v118, v119
	v_add_f32_e32 v0, v0, v120
	v_add_f32_e32 v1, v1, v121
	v_add_f32_e32 v96, v96, v123
	v_add_f32_e32 v3, v3, v122
	v_cvt_pk_bf16_f32 v100, v120, v121
	v_add_f32_e32 v0, v0, v88
	v_add_f32_e32 v1, v1, v89
	v_add_f32_e32 v96, v96, v91
	v_add_f32_e32 v3, v3, v90
	v_cvt_pk_bf16_f32 v101, v122, v123
	v_add_f32_e32 v0, v0, v124
	v_add_f32_e32 v1, v1, v125
	v_add_f32_e32 v96, v96, v127
	v_add_f32_e32 v3, v3, v126
	v_cvt_pk_bf16_f32 v102, v124, v125
	v_add_f32_e32 v0, v0, v92
	v_add_f32_e32 v1, v1, v93
	v_add_f32_e32 v96, v96, v95
	v_add_f32_e32 v3, v3, v94
	v_cvt_pk_bf16_f32 v103, v126, v127
	v_add_f32_e32 v0, v0, v1
	v_add_f32_e32 v1, v3, v96
	v_cvt_pk_bf16_f32 v96, v112, v113
	v_add_f32_e32 v0, v0, v1
	v_cvt_pk_bf16_f32 v80, v80, v81
	v_cvt_pk_bf16_f32 v81, v82, v83
	v_cvt_pk_bf16_f32 v82, v84, v85
	v_cvt_pk_bf16_f32 v83, v86, v87
	v_cvt_pk_bf16_f32 v84, v88, v89
	v_cvt_pk_bf16_f32 v85, v90, v91
	v_cvt_pk_bf16_f32 v86, v92, v93
	v_cvt_pk_bf16_f32 v87, v94, v95
	s_setprio 1
	v_mfma_f32_32x32x16_bf16 v[32:47], v[4:7], v[96:99], v[32:47]
	s_waitcnt lgkmcnt(12)
	v_mfma_f32_32x32x16_bf16 v[16:31], v[8:11], v[96:99], v[16:31]
	s_waitcnt lgkmcnt(10)
	v_mfma_f32_32x32x16_bf16 v[32:47], v[12:15], v[100:103], v[32:47]
	s_waitcnt lgkmcnt(8)
	v_mfma_f32_32x32x16_bf16 v[16:31], v[164:167], v[100:103], v[16:31]
	s_waitcnt lgkmcnt(6)
	v_mfma_f32_32x32x16_bf16 v[32:47], v[168:171], v[80:83], v[32:47]
	s_waitcnt lgkmcnt(4)
	v_mfma_f32_32x32x16_bf16 v[16:31], v[172:175], v[80:83], v[16:31]
	s_waitcnt lgkmcnt(2)
	v_mfma_f32_32x32x16_bf16 v[32:47], v[176:179], v[84:87], v[32:47]
	s_waitcnt lgkmcnt(0)
	v_mfma_f32_32x32x16_bf16 v[16:31], v[180:183], v[84:87], v[16:31]
	s_setprio 0
	s_andn2_b64 vcc, exec, s[54:55]
	s_mov_b64 s[16:17], -1
	s_cbranch_vccnz .LBB0_871
	s_lshl_b64 s[12:13], 1, s2
	s_andn2_b64 s[12:13], s[58:59], s[12:13]
	s_mov_b64 s[16:17], 0
	s_waitcnt vmcnt(1)
	ds_write_b128 v192, v[148:151]
	s_waitcnt vmcnt(0)
	ds_write_b128 v194, v[152:155] offset:18432
	s_waitcnt lgkmcnt(0)
	s_barrier
	s_branch .LBB0_871

.LBB0_962:
	s_or_b64 exec, exec, s[16:17]
	s_nop 0
	s_xor_b64 s[12:13], s[20:21], -1
	v_max3_f32 v0, v96, v97, v80
	v_max3_f32 v1, v98, v99, v81
	v_max3_f32 v0, v0, v82, v83
	v_max3_f32 v1, v1, v102, v103
	v_max3_f32 v0, v0, v100, v101
	v_max3_f32 v1, v1, v86, v87
	v_max3_f32 v0, v0, v84, v85
	v_max3_f32 v1, v1, v106, v107
	v_max3_f32 v0, v0, v104, v105
	v_max3_f32 v1, v1, v90, v91
	v_max3_f32 v0, v0, v88, v89
	v_max3_f32 v1, v1, v110, v111
	v_max3_f32 v0, v0, v108, v109
	v_max3_f32 v1, v1, v94, v95
	v_max3_f32 v0, v0, v92, v93
	v_max_f32_e32 v0, v0, v1
	v_mov_b32_e32 v1, v0
	s_nop 1
	v_permlane32_swap_b32_e32 v0, v1
	v_max_f32_e32 v1, v0, v1
	v_cmp_lt_f32_e32 vcc, s14, v1
	s_or_b64 s[16:17], vcc, s[12:13]
	v_cndmask_b32_e64 v0, 0, 1, s[16:17]
	v_cmp_ne_u32_e32 vcc, 0, v0
	s_cbranch_vccz .LBB0_968
	s_and_saveexec_b64 s[16:17], s[12:13]
	s_xor_b64 s[12:13], exec, s[16:17]
	v_cmp_lg_f32_e64 s[20:21], s5, v1
	s_nop 1
	v_cndmask_b32_e64 v48, 0, v1, s[20:21]
	s_or_saveexec_b64 s[12:13], s[12:13]
	v_mov_b32_e32 v0, 1.0
	s_xor_b64 exec, exec, s[12:13]
	v_max_f32_e32 v0, v1, v1
	v_max_f32_e32 v48, 0, v0
	v_exp_f32_e64 v0, -v48
	s_or_b64 s[20:21], s[20:21], exec
	s_or_b64 exec, exec, s[12:13]
	v_add_f32_e32 v227, v227, v48
	v_xor_b32_e32 v64, 0x80000000, v227
	v_pk_add_f32 v[96:97], v[96:97], v[48:49] op_sel_hi:[1,0] neg_lo:[0,1] neg_hi:[0,1]
	v_pk_add_f32 v[80:81], v[80:81], v[48:49] op_sel_hi:[1,0] neg_lo:[0,1] neg_hi:[0,1]
	v_pk_add_f32 v[98:99], v[98:99], v[48:49] op_sel_hi:[1,0] neg_lo:[0,1] neg_hi:[0,1]
	v_pk_add_f32 v[82:83], v[82:83], v[48:49] op_sel_hi:[1,0] neg_lo:[0,1] neg_hi:[0,1]
	v_pk_add_f32 v[100:101], v[100:101], v[48:49] op_sel_hi:[1,0] neg_lo:[0,1] neg_hi:[0,1]
	v_pk_add_f32 v[84:85], v[84:85], v[48:49] op_sel_hi:[1,0] neg_lo:[0,1] neg_hi:[0,1]
	v_pk_add_f32 v[102:103], v[102:103], v[48:49] op_sel_hi:[1,0] neg_lo:[0,1] neg_hi:[0,1]
	v_pk_add_f32 v[86:87], v[86:87], v[48:49] op_sel_hi:[1,0] neg_lo:[0,1] neg_hi:[0,1]
	v_pk_add_f32 v[104:105], v[104:105], v[48:49] op_sel_hi:[1,0] neg_lo:[0,1] neg_hi:[0,1]
	v_pk_add_f32 v[88:89], v[88:89], v[48:49] op_sel_hi:[1,0] neg_lo:[0,1] neg_hi:[0,1]
	v_pk_add_f32 v[106:107], v[106:107], v[48:49] op_sel_hi:[1,0] neg_lo:[0,1] neg_hi:[0,1]
	v_pk_add_f32 v[90:91], v[90:91], v[48:49] op_sel_hi:[1,0] neg_lo:[0,1] neg_hi:[0,1]
	v_pk_add_f32 v[108:109], v[108:109], v[48:49] op_sel_hi:[1,0] neg_lo:[0,1] neg_hi:[0,1]
	v_pk_add_f32 v[92:93], v[92:93], v[48:49] op_sel_hi:[1,0] neg_lo:[0,1] neg_hi:[0,1]
	v_pk_add_f32 v[110:111], v[110:111], v[48:49] op_sel_hi:[1,0] neg_lo:[0,1] neg_hi:[0,1]
	v_pk_add_f32 v[94:95], v[94:95], v[48:49] op_sel_hi:[1,0] neg_lo:[0,1] neg_hi:[0,1]
	v_mul_f32_e32 v226, v226, v0
	v_pk_mul_f32 v[46:47], v[46:47], v[0:1] op_sel_hi:[1,0]
	v_pk_mul_f32 v[44:45], v[44:45], v[0:1] op_sel_hi:[1,0]
	v_pk_mul_f32 v[42:43], v[42:43], v[0:1] op_sel_hi:[1,0]
	v_pk_mul_f32 v[40:41], v[40:41], v[0:1] op_sel_hi:[1,0]
	v_pk_mul_f32 v[38:39], v[38:39], v[0:1] op_sel_hi:[1,0]
	v_pk_mul_f32 v[36:37], v[36:37], v[0:1] op_sel_hi:[1,0]
	v_pk_mul_f32 v[34:35], v[34:35], v[0:1] op_sel_hi:[1,0]
	v_pk_mul_f32 v[32:33], v[32:33], v[0:1] op_sel_hi:[1,0]
	v_pk_mul_f32 v[30:31], v[30:31], v[0:1] op_sel_hi:[1,0]
	v_pk_mul_f32 v[28:29], v[28:29], v[0:1] op_sel_hi:[1,0]
	v_pk_mul_f32 v[26:27], v[26:27], v[0:1] op_sel_hi:[1,0]
	v_pk_mul_f32 v[24:25], v[24:25], v[0:1] op_sel_hi:[1,0]
	v_pk_mul_f32 v[22:23], v[22:23], v[0:1] op_sel_hi:[1,0]
	v_pk_mul_f32 v[20:21], v[20:21], v[0:1] op_sel_hi:[1,0]
	v_pk_mul_f32 v[18:19], v[18:19], v[0:1] op_sel_hi:[1,0]
	v_pk_mul_f32 v[16:17], v[16:17], v[0:1] op_sel_hi:[1,0]
	v_mov_b32_e32 v65, v64
	v_mov_b32_e32 v66, v64
	v_mov_b32_e32 v67, v64
	v_mov_b32_e32 v68, v64
	v_mov_b32_e32 v69, v64
	v_mov_b32_e32 v70, v64
	v_mov_b32_e32 v71, v64
	v_mov_b32_e32 v72, v64
	v_mov_b32_e32 v73, v64
	v_mov_b32_e32 v74, v64
	v_mov_b32_e32 v75, v64
	v_mov_b32_e32 v76, v64
	v_mov_b32_e32 v77, v64
	v_mov_b32_e32 v78, v64
	v_mov_b32_e32 v79, v64
	v_mov_b32_e32 v63, v64
	v_mov_b32_e32 v62, v64
	v_mov_b32_e32 v61, v64
	v_mov_b32_e32 v60, v64
	v_mov_b32_e32 v59, v64
	v_mov_b32_e32 v58, v64
	v_mov_b32_e32 v57, v64
	v_mov_b32_e32 v56, v64
	v_mov_b32_e32 v55, v64
	v_mov_b32_e32 v54, v64
	v_mov_b32_e32 v53, v64
	v_mov_b32_e32 v52, v64
	v_mov_b32_e32 v51, v64
	v_mov_b32_e32 v50, v64
	v_mov_b32_e32 v49, v64
	v_mov_b32_e32 v48, v64
	s_branch .LBB0_969

.LBB0_969:
	v_exp_f32_e32 v96, v96
	v_exp_f32_e32 v80, v80
	v_exp_f32_e32 v97, v97
	v_exp_f32_e32 v81, v81
	v_exp_f32_e32 v98, v98
	v_exp_f32_e32 v82, v82
	v_exp_f32_e32 v99, v99
	v_exp_f32_e32 v83, v83
	v_exp_f32_e32 v100, v100
	v_exp_f32_e32 v84, v84
	v_exp_f32_e32 v101, v101
	v_exp_f32_e32 v85, v85
	v_exp_f32_e32 v102, v102
	v_exp_f32_e32 v86, v86
	v_exp_f32_e32 v103, v103
	v_exp_f32_e32 v87, v87
	v_exp_f32_e32 v104, v104
	v_exp_f32_e32 v88, v88
	v_exp_f32_e32 v105, v105
	v_exp_f32_e32 v89, v89
	v_exp_f32_e32 v106, v106
	v_exp_f32_e32 v90, v90
	v_exp_f32_e32 v107, v107
	v_exp_f32_e32 v91, v91
	v_exp_f32_e32 v108, v108
	v_exp_f32_e32 v92, v92
	v_exp_f32_e32 v109, v109
	v_exp_f32_e32 v93, v93
	v_exp_f32_e32 v110, v110
	v_exp_f32_e32 v94, v94
	v_exp_f32_e32 v111, v111
	v_exp_f32_e32 v95, v95
	s_mov_b64 s[16:17], -1
	v_add_f32_e32 v0, v96, v80
	v_add_f32_e32 v1, v97, v81
	v_add_f32_e32 v3, v98, v82
	v_add_f32_e32 v112, v99, v83
	v_cvt_pk_bf16_f32 v96, v96, v97
	v_add_f32_e32 v0, v0, v100
	v_add_f32_e32 v1, v1, v101
	v_add_f32_e32 v3, v3, v102
	v_add_f32_e32 v112, v112, v103
	v_cvt_pk_bf16_f32 v97, v98, v99
	v_add_f32_e32 v0, v0, v84
	v_add_f32_e32 v1, v1, v85
	v_add_f32_e32 v3, v3, v86
	v_add_f32_e32 v112, v112, v87
	v_cvt_pk_bf16_f32 v98, v100, v101
	v_add_f32_e32 v0, v0, v104
	v_add_f32_e32 v1, v1, v105
	v_add_f32_e32 v3, v3, v106
	v_add_f32_e32 v112, v112, v107
	v_cvt_pk_bf16_f32 v99, v102, v103
	v_add_f32_e32 v0, v0, v88
	v_add_f32_e32 v1, v1, v89
	v_add_f32_e32 v3, v3, v90
	v_add_f32_e32 v112, v112, v91
	v_cvt_pk_bf16_f32 v100, v104, v105
	v_add_f32_e32 v0, v0, v108
	v_add_f32_e32 v1, v1, v109
	v_add_f32_e32 v3, v3, v110
	v_add_f32_e32 v112, v112, v111
	v_cvt_pk_bf16_f32 v101, v106, v107
	v_add_f32_e32 v0, v0, v92
	v_add_f32_e32 v1, v1, v93
	v_add_f32_e32 v3, v3, v94
	v_add_f32_e32 v112, v112, v95
	v_cvt_pk_bf16_f32 v102, v108, v109
	v_add_f32_e32 v0, v0, v1
	v_add_f32_e32 v1, v3, v112
	v_cvt_pk_bf16_f32 v103, v110, v111
	v_add_f32_e32 v0, v0, v1
	v_cvt_pk_bf16_f32 v80, v80, v81
	v_add_f32_e32 v226, v226, v0
	v_cvt_pk_bf16_f32 v81, v82, v83
	v_cvt_pk_bf16_f32 v82, v84, v85
	v_cvt_pk_bf16_f32 v83, v86, v87
	v_cvt_pk_bf16_f32 v84, v88, v89
	v_cvt_pk_bf16_f32 v85, v90, v91
	v_cvt_pk_bf16_f32 v86, v92, v93
	v_cvt_pk_bf16_f32 v87, v94, v95
	s_setprio 1
	v_mfma_f32_32x32x16_bf16 v[32:47], v[4:7], v[96:99], v[32:47]
	s_waitcnt lgkmcnt(12)
	v_mfma_f32_32x32x16_bf16 v[16:31], v[8:11], v[96:99], v[16:31]
	s_waitcnt lgkmcnt(10)
	v_mfma_f32_32x32x16_bf16 v[32:47], v[12:15], v[100:103], v[32:47]
	s_waitcnt lgkmcnt(8)
	v_mfma_f32_32x32x16_bf16 v[16:31], v[164:167], v[100:103], v[16:31]
	s_waitcnt lgkmcnt(6)
	v_mfma_f32_32x32x16_bf16 v[32:47], v[168:171], v[80:83], v[32:47]
	s_waitcnt lgkmcnt(4)
	v_mfma_f32_32x32x16_bf16 v[16:31], v[172:175], v[80:83], v[16:31]
	s_waitcnt lgkmcnt(2)
	v_mfma_f32_32x32x16_bf16 v[32:47], v[176:179], v[84:87], v[32:47]
	s_waitcnt lgkmcnt(0)
	v_mfma_f32_32x32x16_bf16 v[16:31], v[180:183], v[84:87], v[16:31]
	s_setprio 0
	s_cmp_lt_i32 s28, 0
	s_cbranch_scc1 .LBB0_975
	s_lshl_b64 s[12:13], 1, s0
	s_andn2_b64 s[12:13], s[24:25], s[12:13]
	s_ff1_i32_b64 s30, s[12:13]
	s_cmp_lg_u64 s[12:13], 0
	s_cselect_b32 s29, s30, -1
	s_cmp_lt_i32 s29, 0
	s_waitcnt vmcnt(1)
	ds_write_b128 v192, v[156:159] offset:9216
	s_waitcnt vmcnt(0)
	ds_write_b128 v194, v[160:163] offset:30720
	s_waitcnt lgkmcnt(0)
	s_barrier
	s_cbranch_scc1 .LBB0_972
	v_mad_u64_u32 v[0:1], s[16:17], s29, v243, v[224:225]
	global_load_dwordx4 v[156:159], v[0:1], off offset:1536
	global_load_dwordx4 v[160:163], v[0:1], off offset:1792

.LBB0_982:
	s_or_b64 exec, exec, s[16:17]
	s_nop 0
	s_xor_b64 s[16:17], s[20:21], -1
	v_max3_f32 v0, v80, v81, v64
	v_max3_f32 v1, v82, v83, v65
	v_max3_f32 v0, v0, v66, v67
	v_max3_f32 v1, v1, v86, v87
	v_max3_f32 v0, v0, v84, v85
	v_max3_f32 v1, v1, v70, v71
	v_max3_f32 v0, v0, v68, v69
	v_max3_f32 v1, v1, v90, v91
	v_max3_f32 v0, v0, v88, v89
	v_max3_f32 v1, v1, v74, v75
	v_max3_f32 v0, v0, v72, v73
	v_max3_f32 v1, v1, v94, v95
	v_max3_f32 v0, v0, v92, v93
	v_max3_f32 v1, v1, v78, v79
	v_max3_f32 v0, v0, v76, v77
	v_max_f32_e32 v0, v0, v1
	v_mov_b32_e32 v1, v0
	s_nop 1
	v_permlane32_swap_b32_e32 v0, v1
	v_max_f32_e32 v1, v0, v1
	v_cmp_lt_f32_e32 vcc, s14, v1
	s_or_b64 s[24:25], vcc, s[16:17]
	v_cndmask_b32_e64 v0, 0, 1, s[24:25]
	v_cmp_ne_u32_e32 vcc, 0, v0
	s_cbranch_vccz .LBB0_988
	s_and_saveexec_b64 s[24:25], s[16:17]
	s_xor_b64 s[16:17], exec, s[24:25]
	v_cmp_lg_f32_e64 s[20:21], s5, v1
	s_nop 1
	v_cndmask_b32_e64 v48, 0, v1, s[20:21]
	s_or_saveexec_b64 s[16:17], s[16:17]
	v_mov_b32_e32 v0, 1.0
	s_xor_b64 exec, exec, s[16:17]
	v_max_f32_e32 v0, v1, v1
	v_max_f32_e32 v48, 0, v0
	v_exp_f32_e64 v0, -v48
	s_or_b64 s[20:21], s[20:21], exec
	s_or_b64 exec, exec, s[16:17]
	v_add_f32_e32 v227, v227, v48
	v_xor_b32_e32 v63, 0x80000000, v227
	v_pk_add_f32 v[80:81], v[80:81], v[48:49] op_sel_hi:[1,0] neg_lo:[0,1] neg_hi:[0,1]
	v_pk_add_f32 v[64:65], v[64:65], v[48:49] op_sel_hi:[1,0] neg_lo:[0,1] neg_hi:[0,1]
	v_pk_add_f32 v[82:83], v[82:83], v[48:49] op_sel_hi:[1,0] neg_lo:[0,1] neg_hi:[0,1]
	v_pk_add_f32 v[66:67], v[66:67], v[48:49] op_sel_hi:[1,0] neg_lo:[0,1] neg_hi:[0,1]
	v_pk_add_f32 v[84:85], v[84:85], v[48:49] op_sel_hi:[1,0] neg_lo:[0,1] neg_hi:[0,1]
	v_pk_add_f32 v[68:69], v[68:69], v[48:49] op_sel_hi:[1,0] neg_lo:[0,1] neg_hi:[0,1]
	v_pk_add_f32 v[86:87], v[86:87], v[48:49] op_sel_hi:[1,0] neg_lo:[0,1] neg_hi:[0,1]
	v_pk_add_f32 v[70:71], v[70:71], v[48:49] op_sel_hi:[1,0] neg_lo:[0,1] neg_hi:[0,1]
	v_pk_add_f32 v[88:89], v[88:89], v[48:49] op_sel_hi:[1,0] neg_lo:[0,1] neg_hi:[0,1]
	v_pk_add_f32 v[72:73], v[72:73], v[48:49] op_sel_hi:[1,0] neg_lo:[0,1] neg_hi:[0,1]
	v_pk_add_f32 v[90:91], v[90:91], v[48:49] op_sel_hi:[1,0] neg_lo:[0,1] neg_hi:[0,1]
	v_pk_add_f32 v[74:75], v[74:75], v[48:49] op_sel_hi:[1,0] neg_lo:[0,1] neg_hi:[0,1]
	v_pk_add_f32 v[92:93], v[92:93], v[48:49] op_sel_hi:[1,0] neg_lo:[0,1] neg_hi:[0,1]
	v_pk_add_f32 v[76:77], v[76:77], v[48:49] op_sel_hi:[1,0] neg_lo:[0,1] neg_hi:[0,1]
	v_pk_add_f32 v[94:95], v[94:95], v[48:49] op_sel_hi:[1,0] neg_lo:[0,1] neg_hi:[0,1]
	v_pk_add_f32 v[78:79], v[78:79], v[48:49] op_sel_hi:[1,0] neg_lo:[0,1] neg_hi:[0,1]
	v_mul_f32_e32 v226, v226, v0
	v_pk_mul_f32 v[46:47], v[46:47], v[0:1] op_sel_hi:[1,0]
	v_pk_mul_f32 v[44:45], v[44:45], v[0:1] op_sel_hi:[1,0]
	v_pk_mul_f32 v[42:43], v[42:43], v[0:1] op_sel_hi:[1,0]
	v_pk_mul_f32 v[40:41], v[40:41], v[0:1] op_sel_hi:[1,0]
	v_pk_mul_f32 v[38:39], v[38:39], v[0:1] op_sel_hi:[1,0]
	v_pk_mul_f32 v[36:37], v[36:37], v[0:1] op_sel_hi:[1,0]
	v_pk_mul_f32 v[34:35], v[34:35], v[0:1] op_sel_hi:[1,0]
	v_pk_mul_f32 v[32:33], v[32:33], v[0:1] op_sel_hi:[1,0]
	v_pk_mul_f32 v[30:31], v[30:31], v[0:1] op_sel_hi:[1,0]
	v_pk_mul_f32 v[28:29], v[28:29], v[0:1] op_sel_hi:[1,0]
	v_pk_mul_f32 v[26:27], v[26:27], v[0:1] op_sel_hi:[1,0]
	v_pk_mul_f32 v[24:25], v[24:25], v[0:1] op_sel_hi:[1,0]
	v_pk_mul_f32 v[22:23], v[22:23], v[0:1] op_sel_hi:[1,0]
	v_pk_mul_f32 v[20:21], v[20:21], v[0:1] op_sel_hi:[1,0]
	v_pk_mul_f32 v[18:19], v[18:19], v[0:1] op_sel_hi:[1,0]
	v_pk_mul_f32 v[16:17], v[16:17], v[0:1] op_sel_hi:[1,0]
	v_mov_b32_e32 v62, v63
	v_mov_b32_e32 v61, v63
	v_mov_b32_e32 v60, v63
	v_mov_b32_e32 v59, v63
	v_mov_b32_e32 v58, v63
	v_mov_b32_e32 v57, v63
	v_mov_b32_e32 v56, v63
	v_mov_b32_e32 v55, v63
	v_mov_b32_e32 v54, v63
	v_mov_b32_e32 v53, v63
	v_mov_b32_e32 v52, v63
	v_mov_b32_e32 v51, v63
	v_mov_b32_e32 v50, v63
	v_mov_b32_e32 v49, v63
	v_mov_b32_e32 v48, v63
.LBB0_988:
	v_exp_f32_e32 v80, v80
	v_exp_f32_e32 v64, v64
	v_exp_f32_e32 v81, v81
	v_exp_f32_e32 v65, v65
	v_exp_f32_e32 v82, v82
	v_exp_f32_e32 v66, v66
	v_exp_f32_e32 v83, v83
	v_exp_f32_e32 v67, v67
	v_exp_f32_e32 v84, v84
	v_exp_f32_e32 v68, v68
	v_exp_f32_e32 v85, v85
	v_exp_f32_e32 v69, v69
	v_exp_f32_e32 v86, v86
	v_exp_f32_e32 v70, v70
	v_exp_f32_e32 v87, v87
	v_exp_f32_e32 v71, v71
	v_exp_f32_e32 v88, v88
	v_exp_f32_e32 v72, v72
	v_exp_f32_e32 v89, v89
	v_exp_f32_e32 v73, v73
	v_exp_f32_e32 v90, v90
	v_exp_f32_e32 v74, v74
	v_exp_f32_e32 v91, v91
	v_exp_f32_e32 v75, v75
	v_exp_f32_e32 v92, v92
	v_exp_f32_e32 v76, v76
	v_exp_f32_e32 v93, v93
	v_exp_f32_e32 v77, v77
	v_exp_f32_e32 v94, v94
	v_exp_f32_e32 v78, v78
	v_exp_f32_e32 v95, v95
	v_exp_f32_e32 v79, v79
	v_add_f32_e32 v0, v80, v64
	v_add_f32_e32 v1, v81, v65
	v_add_f32_e32 v3, v82, v66
	v_add_f32_e32 v96, v83, v67
	v_cvt_pk_bf16_f32 v80, v80, v81
	v_add_f32_e32 v0, v0, v84
	v_add_f32_e32 v1, v1, v85
	v_add_f32_e32 v3, v3, v86
	v_add_f32_e32 v96, v96, v87
	v_cvt_pk_bf16_f32 v81, v82, v83
	v_add_f32_e32 v0, v0, v68
	v_add_f32_e32 v1, v1, v69
	v_add_f32_e32 v3, v3, v70
	v_add_f32_e32 v96, v96, v71
	v_cvt_pk_bf16_f32 v82, v84, v85
	v_add_f32_e32 v0, v0, v88
	v_add_f32_e32 v1, v1, v89
	v_add_f32_e32 v3, v3, v90
	v_add_f32_e32 v96, v96, v91
	v_cvt_pk_bf16_f32 v83, v86, v87
	v_add_f32_e32 v0, v0, v72
	v_add_f32_e32 v1, v1, v73
	v_add_f32_e32 v3, v3, v74
	v_add_f32_e32 v96, v96, v75
	v_cvt_pk_bf16_f32 v84, v88, v89
	v_add_f32_e32 v0, v0, v92
	v_add_f32_e32 v1, v1, v93
	v_add_f32_e32 v3, v3, v94
	v_add_f32_e32 v96, v96, v95
	v_cvt_pk_bf16_f32 v85, v90, v91
	v_add_f32_e32 v0, v0, v76
	v_add_f32_e32 v1, v1, v77
	v_add_f32_e32 v3, v3, v78
	v_add_f32_e32 v96, v96, v79
	v_cvt_pk_bf16_f32 v86, v92, v93
	v_add_f32_e32 v0, v0, v1
	v_add_f32_e32 v1, v3, v96
	v_cvt_pk_bf16_f32 v87, v94, v95
	v_add_f32_e32 v0, v0, v1
	v_cvt_pk_bf16_f32 v64, v64, v65
	v_cvt_pk_bf16_f32 v65, v66, v67
	v_cvt_pk_bf16_f32 v66, v68, v69
	v_cvt_pk_bf16_f32 v67, v70, v71
	v_cvt_pk_bf16_f32 v68, v72, v73
	v_cvt_pk_bf16_f32 v69, v74, v75
	v_cvt_pk_bf16_f32 v70, v76, v77
	v_cvt_pk_bf16_f32 v71, v78, v79
	s_setprio 1
	v_mfma_f32_32x32x16_bf16 v[32:47], v[4:7], v[80:83], v[32:47]
	s_waitcnt lgkmcnt(12)
	v_mfma_f32_32x32x16_bf16 v[16:31], v[8:11], v[80:83], v[16:31]
	s_waitcnt lgkmcnt(10)
	v_mfma_f32_32x32x16_bf16 v[32:47], v[12:15], v[84:87], v[32:47]
	s_waitcnt lgkmcnt(8)
	v_mfma_f32_32x32x16_bf16 v[16:31], v[164:167], v[84:87], v[16:31]
	s_waitcnt lgkmcnt(6)
	v_mfma_f32_32x32x16_bf16 v[32:47], v[168:171], v[64:67], v[32:47]
	s_waitcnt lgkmcnt(4)
	v_mfma_f32_32x32x16_bf16 v[16:31], v[172:175], v[64:67], v[16:31]
	s_waitcnt lgkmcnt(2)
	v_mfma_f32_32x32x16_bf16 v[32:47], v[176:179], v[68:71], v[32:47]
	s_waitcnt lgkmcnt(0)
	v_mfma_f32_32x32x16_bf16 v[16:31], v[180:183], v[68:71], v[16:31]
	s_setprio 0
	s_andn2_b64 vcc, exec, s[22:23]
	s_mov_b64 s[16:17], -1
	s_cbranch_vccnz .LBB0_950
	s_lshl_b64 s[16:17], 1, s30
	s_andn2_b64 s[24:25], s[12:13], s[16:17]
	s_mov_b64 s[16:17], 0
	s_waitcnt vmcnt(1)
	ds_write_b128 v192, v[148:151]
	s_waitcnt vmcnt(0)
	ds_write_b128 v194, v[152:155] offset:18432
	s_waitcnt lgkmcnt(0)
	s_barrier
	s_branch .LBB0_950

.LBB0_1003:
	s_nop 3
	s_xor_b64 s[16:17], s[94:95], -1
	v_max3_f32 v0, v80, v81, v96
	v_max3_f32 v1, v82, v83, v97
	v_max3_f32 v0, v0, v98, v99
	v_max3_f32 v1, v1, v86, v87
	v_max3_f32 v0, v0, v84, v85
	v_max3_f32 v1, v1, v102, v103
	v_max3_f32 v0, v0, v100, v101
	v_max3_f32 v1, v1, v90, v91
	v_max3_f32 v0, v0, v88, v89
	v_max3_f32 v1, v1, v106, v107
	v_max3_f32 v0, v0, v104, v105
	v_max3_f32 v1, v1, v94, v95
	v_max3_f32 v0, v0, v92, v93
	v_max3_f32 v1, v1, v110, v111
	v_max3_f32 v0, v0, v108, v109
	v_max_f32_e32 v0, v0, v1
	v_mov_b32_e32 v1, v0
	s_nop 1
	v_permlane32_swap_b32_e32 v0, v1
	v_max_f32_e32 v1, v0, v1
	v_cmp_lt_f32_e32 vcc, s14, v1
	s_or_b64 s[18:19], vcc, s[16:17]
	v_cndmask_b32_e64 v0, 0, 1, s[18:19]
	v_cmp_ne_u32_e32 vcc, 0, v0
	s_cbranch_vccz .LBB0_1009
	s_and_saveexec_b64 s[18:19], s[16:17]
	s_xor_b64 s[16:17], exec, s[18:19]
	v_cmp_lg_f32_e64 s[94:95], s5, v1
	s_nop 1
	v_cndmask_b32_e64 v48, 0, v1, s[94:95]
	s_or_saveexec_b64 s[16:17], s[16:17]
	v_mov_b32_e32 v0, 1.0
	s_xor_b64 exec, exec, s[16:17]
	v_max_f32_e32 v0, v1, v1
	v_max_f32_e32 v48, 0, v0
	v_exp_f32_e64 v0, -v48
	s_or_b64 s[94:95], s[94:95], exec
	s_or_b64 exec, exec, s[16:17]
	v_add_f32_e32 v248, v248, v48
	v_xor_b32_e32 v64, 0x80000000, v248
	v_pk_add_f32 v[80:81], v[80:81], v[48:49] op_sel_hi:[1,0] neg_lo:[0,1] neg_hi:[0,1]
	v_pk_add_f32 v[96:97], v[96:97], v[48:49] op_sel_hi:[1,0] neg_lo:[0,1] neg_hi:[0,1]
	v_pk_add_f32 v[82:83], v[82:83], v[48:49] op_sel_hi:[1,0] neg_lo:[0,1] neg_hi:[0,1]
	v_pk_add_f32 v[98:99], v[98:99], v[48:49] op_sel_hi:[1,0] neg_lo:[0,1] neg_hi:[0,1]
	v_pk_add_f32 v[84:85], v[84:85], v[48:49] op_sel_hi:[1,0] neg_lo:[0,1] neg_hi:[0,1]
	v_pk_add_f32 v[100:101], v[100:101], v[48:49] op_sel_hi:[1,0] neg_lo:[0,1] neg_hi:[0,1]
	v_pk_add_f32 v[86:87], v[86:87], v[48:49] op_sel_hi:[1,0] neg_lo:[0,1] neg_hi:[0,1]
	v_pk_add_f32 v[102:103], v[102:103], v[48:49] op_sel_hi:[1,0] neg_lo:[0,1] neg_hi:[0,1]
	v_pk_add_f32 v[88:89], v[88:89], v[48:49] op_sel_hi:[1,0] neg_lo:[0,1] neg_hi:[0,1]
	v_pk_add_f32 v[104:105], v[104:105], v[48:49] op_sel_hi:[1,0] neg_lo:[0,1] neg_hi:[0,1]
	v_pk_add_f32 v[90:91], v[90:91], v[48:49] op_sel_hi:[1,0] neg_lo:[0,1] neg_hi:[0,1]
	v_pk_add_f32 v[106:107], v[106:107], v[48:49] op_sel_hi:[1,0] neg_lo:[0,1] neg_hi:[0,1]
	v_pk_add_f32 v[92:93], v[92:93], v[48:49] op_sel_hi:[1,0] neg_lo:[0,1] neg_hi:[0,1]
	v_pk_add_f32 v[108:109], v[108:109], v[48:49] op_sel_hi:[1,0] neg_lo:[0,1] neg_hi:[0,1]
	v_pk_add_f32 v[94:95], v[94:95], v[48:49] op_sel_hi:[1,0] neg_lo:[0,1] neg_hi:[0,1]
	v_pk_add_f32 v[110:111], v[110:111], v[48:49] op_sel_hi:[1,0] neg_lo:[0,1] neg_hi:[0,1]
	v_mul_f32_e32 v222, v222, v0
	v_pk_mul_f32 v[46:47], v[46:47], v[0:1] op_sel_hi:[1,0]
	v_pk_mul_f32 v[44:45], v[44:45], v[0:1] op_sel_hi:[1,0]
	v_pk_mul_f32 v[42:43], v[42:43], v[0:1] op_sel_hi:[1,0]
	v_pk_mul_f32 v[40:41], v[40:41], v[0:1] op_sel_hi:[1,0]
	v_pk_mul_f32 v[38:39], v[38:39], v[0:1] op_sel_hi:[1,0]
	v_pk_mul_f32 v[36:37], v[36:37], v[0:1] op_sel_hi:[1,0]
	v_pk_mul_f32 v[34:35], v[34:35], v[0:1] op_sel_hi:[1,0]
	v_pk_mul_f32 v[32:33], v[32:33], v[0:1] op_sel_hi:[1,0]
	v_pk_mul_f32 v[30:31], v[30:31], v[0:1] op_sel_hi:[1,0]
	v_pk_mul_f32 v[28:29], v[28:29], v[0:1] op_sel_hi:[1,0]
	v_pk_mul_f32 v[26:27], v[26:27], v[0:1] op_sel_hi:[1,0]
	v_pk_mul_f32 v[24:25], v[24:25], v[0:1] op_sel_hi:[1,0]
	v_pk_mul_f32 v[22:23], v[22:23], v[0:1] op_sel_hi:[1,0]
	v_pk_mul_f32 v[20:21], v[20:21], v[0:1] op_sel_hi:[1,0]
	v_pk_mul_f32 v[18:19], v[18:19], v[0:1] op_sel_hi:[1,0]
	v_pk_mul_f32 v[16:17], v[16:17], v[0:1] op_sel_hi:[1,0]
	v_mov_b32_e32 v65, v64
	v_mov_b32_e32 v66, v64
	v_mov_b32_e32 v67, v64
	v_mov_b32_e32 v68, v64
	v_mov_b32_e32 v69, v64
	v_mov_b32_e32 v70, v64
	v_mov_b32_e32 v71, v64
	v_mov_b32_e32 v72, v64
	v_mov_b32_e32 v73, v64
	v_mov_b32_e32 v74, v64
	v_mov_b32_e32 v75, v64
	v_mov_b32_e32 v76, v64
	v_mov_b32_e32 v77, v64
	v_mov_b32_e32 v78, v64
	v_mov_b32_e32 v79, v64
	v_mov_b32_e32 v63, v64
	v_mov_b32_e32 v62, v64
	v_mov_b32_e32 v61, v64
	v_mov_b32_e32 v60, v64
	v_mov_b32_e32 v59, v64
	v_mov_b32_e32 v58, v64
	v_mov_b32_e32 v57, v64
	v_mov_b32_e32 v56, v64
	v_mov_b32_e32 v55, v64
	v_mov_b32_e32 v54, v64
	v_mov_b32_e32 v53, v64
	v_mov_b32_e32 v52, v64
	v_mov_b32_e32 v51, v64
	v_mov_b32_e32 v50, v64
	v_mov_b32_e32 v49, v64
	v_mov_b32_e32 v48, v64
	s_branch .LBB0_1010

.LBB0_1010:
	v_exp_f32_e32 v112, v80
	v_exp_f32_e32 v80, v96
	v_exp_f32_e32 v113, v81
	v_exp_f32_e32 v81, v97
	v_exp_f32_e32 v114, v82
	v_exp_f32_e32 v82, v98
	v_exp_f32_e32 v115, v83
	v_exp_f32_e32 v83, v99
	v_exp_f32_e32 v116, v84
	v_exp_f32_e32 v84, v100
	v_exp_f32_e32 v117, v85
	v_exp_f32_e32 v85, v101
	v_exp_f32_e32 v118, v86
	v_exp_f32_e32 v86, v102
	v_exp_f32_e32 v119, v87
	v_exp_f32_e32 v87, v103
	v_exp_f32_e32 v120, v88
	v_exp_f32_e32 v88, v104
	v_exp_f32_e32 v121, v89
	v_exp_f32_e32 v89, v105
	v_exp_f32_e32 v122, v90
	v_exp_f32_e32 v90, v106
	v_exp_f32_e32 v123, v91
	v_exp_f32_e32 v91, v107
	v_exp_f32_e32 v124, v92
	v_exp_f32_e32 v92, v108
	v_exp_f32_e32 v125, v93
	v_exp_f32_e32 v93, v109
	v_exp_f32_e32 v126, v94
	v_exp_f32_e32 v94, v110
	v_exp_f32_e32 v127, v95
	v_exp_f32_e32 v95, v111
	s_mov_b64 s[16:17], -1
	v_add_f32_e32 v0, v112, v80
	v_add_f32_e32 v1, v113, v81
	v_add_f32_e32 v3, v114, v82
	v_add_f32_e32 v96, v115, v83
	v_cvt_pk_bf16_f32 v97, v114, v115
	v_add_f32_e32 v0, v0, v116
	v_add_f32_e32 v1, v1, v117
	v_add_f32_e32 v3, v3, v118
	v_add_f32_e32 v96, v96, v119
	v_cvt_pk_bf16_f32 v98, v116, v117
	v_add_f32_e32 v0, v0, v84
	v_add_f32_e32 v1, v1, v85
	v_add_f32_e32 v3, v3, v86
	v_add_f32_e32 v96, v96, v87
	v_cvt_pk_bf16_f32 v99, v118, v119
	v_add_f32_e32 v0, v0, v120
	v_add_f32_e32 v1, v1, v121
	v_add_f32_e32 v3, v3, v122
	v_add_f32_e32 v96, v96, v123
	v_cvt_pk_bf16_f32 v100, v120, v121
	v_add_f32_e32 v0, v0, v88
	v_add_f32_e32 v1, v1, v89
	v_add_f32_e32 v3, v3, v90
	v_add_f32_e32 v96, v96, v91
	v_cvt_pk_bf16_f32 v101, v122, v123
	v_add_f32_e32 v0, v0, v124
	v_add_f32_e32 v1, v1, v125
	v_add_f32_e32 v3, v3, v126
	v_add_f32_e32 v96, v96, v127
	v_cvt_pk_bf16_f32 v102, v124, v125
	v_add_f32_e32 v0, v0, v92
	v_add_f32_e32 v1, v1, v93
	v_add_f32_e32 v3, v3, v94
	v_add_f32_e32 v96, v96, v95
	v_cvt_pk_bf16_f32 v103, v126, v127
	v_add_f32_e32 v0, v0, v1
	v_add_f32_e32 v1, v3, v96
	v_cvt_pk_bf16_f32 v96, v112, v113
	v_add_f32_e32 v0, v0, v1
	v_cvt_pk_bf16_f32 v80, v80, v81
	v_add_f32_e32 v222, v222, v0
	v_cvt_pk_bf16_f32 v81, v82, v83
	v_cvt_pk_bf16_f32 v82, v84, v85
	v_cvt_pk_bf16_f32 v83, v86, v87
	v_cvt_pk_bf16_f32 v84, v88, v89
	v_cvt_pk_bf16_f32 v85, v90, v91
	v_cvt_pk_bf16_f32 v86, v92, v93
	v_cvt_pk_bf16_f32 v87, v94, v95
	s_setprio 1
	v_mfma_f32_32x32x16_bf16 v[32:47], v[4:7], v[96:99], v[32:47]
	s_waitcnt lgkmcnt(12)
	v_mfma_f32_32x32x16_bf16 v[16:31], v[8:11], v[96:99], v[16:31]
	s_waitcnt lgkmcnt(10)
	v_mfma_f32_32x32x16_bf16 v[32:47], v[12:15], v[100:103], v[32:47]
	s_waitcnt lgkmcnt(8)
	v_mfma_f32_32x32x16_bf16 v[16:31], v[164:167], v[100:103], v[16:31]
	s_waitcnt lgkmcnt(6)
	v_mfma_f32_32x32x16_bf16 v[32:47], v[168:171], v[80:83], v[32:47]
	s_waitcnt lgkmcnt(4)
	v_mfma_f32_32x32x16_bf16 v[16:31], v[172:175], v[80:83], v[16:31]
	s_waitcnt lgkmcnt(2)
	v_mfma_f32_32x32x16_bf16 v[32:47], v[176:179], v[84:87], v[32:47]
	s_waitcnt lgkmcnt(0)
	v_mfma_f32_32x32x16_bf16 v[16:31], v[180:183], v[84:87], v[16:31]
	s_setprio 0
	s_cmp_lt_i32 s33, 0
	s_cbranch_scc1 .LBB0_1025
	s_lshl_b64 s[16:17], 1, s0
	s_andn2_b64 s[86:87], s[12:13], s[16:17]
	s_ff1_i32_b64 s96, s[86:87]
	s_cmp_lg_u64 s[86:87], 0
	s_cselect_b32 s2, s96, -1
	s_cmp_lt_i32 s2, 0
	s_waitcnt vmcnt(1)
	ds_write_b128 v192, v[156:159] offset:9216
	s_waitcnt vmcnt(0)
	ds_write_b128 v194, v[160:163] offset:30720
	s_waitcnt lgkmcnt(0)
	s_barrier
	s_cbranch_scc1 .LBB0_1013
	v_mad_u64_u32 v[0:1], s[12:13], s2, v243, v[228:229]
	global_load_dwordx4 v[156:159], v[0:1], off offset:2048
	global_load_dwordx4 v[160:163], v[0:1], off offset:2304

.LBB0_1017:
	s_nop 3
	s_xor_b64 s[12:13], s[94:95], -1
	v_max3_f32 v0, v80, v81, v64
	v_max3_f32 v1, v82, v83, v65
	v_max3_f32 v0, v0, v66, v67
	v_max3_f32 v1, v1, v86, v87
	v_max3_f32 v0, v0, v84, v85
	v_max3_f32 v1, v1, v70, v71
	v_max3_f32 v0, v0, v68, v69
	v_max3_f32 v1, v1, v90, v91
	v_max3_f32 v0, v0, v88, v89
	v_max3_f32 v1, v1, v74, v75
	v_max3_f32 v0, v0, v72, v73
	v_max3_f32 v1, v1, v94, v95
	v_max3_f32 v0, v0, v92, v93
	v_max3_f32 v1, v1, v78, v79
	v_max3_f32 v0, v0, v76, v77
	v_max_f32_e32 v0, v0, v1
	v_mov_b32_e32 v1, v0
	s_nop 1
	v_permlane32_swap_b32_e32 v0, v1
	v_max_f32_e32 v1, v0, v1
	v_cmp_lt_f32_e32 vcc, s14, v1
	s_or_b64 s[16:17], vcc, s[12:13]
	v_cndmask_b32_e64 v0, 0, 1, s[16:17]
	v_cmp_ne_u32_e32 vcc, 0, v0
	s_cbranch_vccz .LBB0_1023
	s_and_saveexec_b64 s[16:17], s[12:13]
	s_xor_b64 s[12:13], exec, s[16:17]
	v_cmp_lg_f32_e64 s[94:95], s5, v1
	s_nop 1
	v_cndmask_b32_e64 v48, 0, v1, s[94:95]
	s_or_saveexec_b64 s[12:13], s[12:13]
	v_mov_b32_e32 v0, 1.0
	s_xor_b64 exec, exec, s[12:13]
	v_max_f32_e32 v0, v1, v1
	v_max_f32_e32 v48, 0, v0
	v_exp_f32_e64 v0, -v48
	s_or_b64 s[94:95], s[94:95], exec
	s_or_b64 exec, exec, s[12:13]
	v_add_f32_e32 v248, v248, v48
	v_xor_b32_e32 v63, 0x80000000, v248
	v_pk_add_f32 v[80:81], v[80:81], v[48:49] op_sel_hi:[1,0] neg_lo:[0,1] neg_hi:[0,1]
	v_pk_add_f32 v[64:65], v[64:65], v[48:49] op_sel_hi:[1,0] neg_lo:[0,1] neg_hi:[0,1]
	v_pk_add_f32 v[82:83], v[82:83], v[48:49] op_sel_hi:[1,0] neg_lo:[0,1] neg_hi:[0,1]
	v_pk_add_f32 v[66:67], v[66:67], v[48:49] op_sel_hi:[1,0] neg_lo:[0,1] neg_hi:[0,1]
	v_pk_add_f32 v[84:85], v[84:85], v[48:49] op_sel_hi:[1,0] neg_lo:[0,1] neg_hi:[0,1]
	v_pk_add_f32 v[68:69], v[68:69], v[48:49] op_sel_hi:[1,0] neg_lo:[0,1] neg_hi:[0,1]
	v_pk_add_f32 v[86:87], v[86:87], v[48:49] op_sel_hi:[1,0] neg_lo:[0,1] neg_hi:[0,1]
	v_pk_add_f32 v[70:71], v[70:71], v[48:49] op_sel_hi:[1,0] neg_lo:[0,1] neg_hi:[0,1]
	v_pk_add_f32 v[88:89], v[88:89], v[48:49] op_sel_hi:[1,0] neg_lo:[0,1] neg_hi:[0,1]
	v_pk_add_f32 v[72:73], v[72:73], v[48:49] op_sel_hi:[1,0] neg_lo:[0,1] neg_hi:[0,1]
	v_pk_add_f32 v[90:91], v[90:91], v[48:49] op_sel_hi:[1,0] neg_lo:[0,1] neg_hi:[0,1]
	v_pk_add_f32 v[74:75], v[74:75], v[48:49] op_sel_hi:[1,0] neg_lo:[0,1] neg_hi:[0,1]
	v_pk_add_f32 v[92:93], v[92:93], v[48:49] op_sel_hi:[1,0] neg_lo:[0,1] neg_hi:[0,1]
	v_pk_add_f32 v[76:77], v[76:77], v[48:49] op_sel_hi:[1,0] neg_lo:[0,1] neg_hi:[0,1]
	v_pk_add_f32 v[94:95], v[94:95], v[48:49] op_sel_hi:[1,0] neg_lo:[0,1] neg_hi:[0,1]
	v_pk_add_f32 v[78:79], v[78:79], v[48:49] op_sel_hi:[1,0] neg_lo:[0,1] neg_hi:[0,1]
	v_mul_f32_e32 v222, v222, v0
	v_pk_mul_f32 v[46:47], v[46:47], v[0:1] op_sel_hi:[1,0]
	v_pk_mul_f32 v[44:45], v[44:45], v[0:1] op_sel_hi:[1,0]
	v_pk_mul_f32 v[42:43], v[42:43], v[0:1] op_sel_hi:[1,0]
	v_pk_mul_f32 v[40:41], v[40:41], v[0:1] op_sel_hi:[1,0]
	v_pk_mul_f32 v[38:39], v[38:39], v[0:1] op_sel_hi:[1,0]
	v_pk_mul_f32 v[36:37], v[36:37], v[0:1] op_sel_hi:[1,0]
	v_pk_mul_f32 v[34:35], v[34:35], v[0:1] op_sel_hi:[1,0]
	v_pk_mul_f32 v[32:33], v[32:33], v[0:1] op_sel_hi:[1,0]
	v_pk_mul_f32 v[30:31], v[30:31], v[0:1] op_sel_hi:[1,0]
	v_pk_mul_f32 v[28:29], v[28:29], v[0:1] op_sel_hi:[1,0]
	v_pk_mul_f32 v[26:27], v[26:27], v[0:1] op_sel_hi:[1,0]
	v_pk_mul_f32 v[24:25], v[24:25], v[0:1] op_sel_hi:[1,0]
	v_pk_mul_f32 v[22:23], v[22:23], v[0:1] op_sel_hi:[1,0]
	v_pk_mul_f32 v[20:21], v[20:21], v[0:1] op_sel_hi:[1,0]
	v_pk_mul_f32 v[18:19], v[18:19], v[0:1] op_sel_hi:[1,0]
	v_pk_mul_f32 v[16:17], v[16:17], v[0:1] op_sel_hi:[1,0]
	v_mov_b32_e32 v62, v63
	v_mov_b32_e32 v61, v63
	v_mov_b32_e32 v60, v63
	v_mov_b32_e32 v59, v63
	v_mov_b32_e32 v58, v63
	v_mov_b32_e32 v57, v63
	v_mov_b32_e32 v56, v63
	v_mov_b32_e32 v55, v63
	v_mov_b32_e32 v54, v63
	v_mov_b32_e32 v53, v63
	v_mov_b32_e32 v52, v63
	v_mov_b32_e32 v51, v63
	v_mov_b32_e32 v50, v63
	v_mov_b32_e32 v49, v63
	v_mov_b32_e32 v48, v63
.LBB0_1023:
	v_exp_f32_e32 v80, v80
	v_exp_f32_e32 v64, v64
	v_exp_f32_e32 v81, v81
	v_exp_f32_e32 v65, v65
	v_exp_f32_e32 v82, v82
	v_exp_f32_e32 v66, v66
	v_exp_f32_e32 v83, v83
	v_exp_f32_e32 v67, v67
	v_exp_f32_e32 v84, v84
	v_exp_f32_e32 v68, v68
	v_exp_f32_e32 v85, v85
	v_exp_f32_e32 v69, v69
	v_exp_f32_e32 v86, v86
	v_exp_f32_e32 v70, v70
	v_exp_f32_e32 v87, v87
	v_exp_f32_e32 v71, v71
	v_exp_f32_e32 v88, v88
	v_exp_f32_e32 v72, v72
	v_exp_f32_e32 v89, v89
	v_exp_f32_e32 v73, v73
	v_exp_f32_e32 v90, v90
	v_exp_f32_e32 v74, v74
	v_exp_f32_e32 v91, v91
	v_exp_f32_e32 v75, v75
	v_exp_f32_e32 v92, v92
	v_exp_f32_e32 v76, v76
	v_exp_f32_e32 v93, v93
	v_exp_f32_e32 v77, v77
	v_exp_f32_e32 v94, v94
	v_exp_f32_e32 v78, v78
	v_exp_f32_e32 v95, v95
	v_exp_f32_e32 v79, v79
	v_add_f32_e32 v0, v80, v64
	v_add_f32_e32 v1, v81, v65
	v_add_f32_e32 v3, v82, v66
	v_add_f32_e32 v116, v83, v67
	v_cvt_pk_bf16_f32 v80, v80, v81
	v_add_f32_e32 v0, v0, v84
	v_add_f32_e32 v1, v1, v85
	v_add_f32_e32 v3, v3, v86
	v_add_f32_e32 v116, v116, v87
	v_cvt_pk_bf16_f32 v81, v82, v83
	v_add_f32_e32 v0, v0, v68
	v_add_f32_e32 v1, v1, v69
	v_add_f32_e32 v3, v3, v70
	v_add_f32_e32 v116, v116, v71
	v_cvt_pk_bf16_f32 v82, v84, v85
	v_add_f32_e32 v0, v0, v88
	v_add_f32_e32 v1, v1, v89
	v_add_f32_e32 v3, v3, v90
	v_add_f32_e32 v116, v116, v91
	v_cvt_pk_bf16_f32 v83, v86, v87
	v_add_f32_e32 v0, v0, v72
	v_add_f32_e32 v1, v1, v73
	v_add_f32_e32 v3, v3, v74
	v_add_f32_e32 v116, v116, v75
	v_cvt_pk_bf16_f32 v84, v88, v89
	v_add_f32_e32 v0, v0, v92
	v_add_f32_e32 v1, v1, v93
	v_add_f32_e32 v3, v3, v94
	v_add_f32_e32 v116, v116, v95
	v_cvt_pk_bf16_f32 v85, v90, v91
	v_add_f32_e32 v0, v0, v76
	v_add_f32_e32 v1, v1, v77
	v_add_f32_e32 v3, v3, v78
	v_add_f32_e32 v116, v116, v79
	v_cvt_pk_bf16_f32 v86, v92, v93
	v_add_f32_e32 v0, v0, v1
	v_add_f32_e32 v1, v3, v116
	v_cvt_pk_bf16_f32 v87, v94, v95
	v_add_f32_e32 v0, v0, v1
	v_cvt_pk_bf16_f32 v64, v64, v65
	v_cvt_pk_bf16_f32 v65, v66, v67
	v_cvt_pk_bf16_f32 v66, v68, v69
	v_cvt_pk_bf16_f32 v67, v70, v71
	v_cvt_pk_bf16_f32 v68, v72, v73
	v_cvt_pk_bf16_f32 v69, v74, v75
	v_cvt_pk_bf16_f32 v70, v76, v77
	v_cvt_pk_bf16_f32 v71, v78, v79
	s_setprio 1
	v_mfma_f32_32x32x16_bf16 v[32:47], v[4:7], v[80:83], v[32:47]
	s_waitcnt lgkmcnt(12)
	v_mfma_f32_32x32x16_bf16 v[16:31], v[8:11], v[80:83], v[16:31]
	s_waitcnt lgkmcnt(10)
	v_mfma_f32_32x32x16_bf16 v[32:47], v[12:15], v[84:87], v[32:47]
	s_waitcnt lgkmcnt(8)
	v_mfma_f32_32x32x16_bf16 v[16:31], v[96:99], v[84:87], v[16:31]
	s_waitcnt lgkmcnt(6)
	v_mfma_f32_32x32x16_bf16 v[32:47], v[100:103], v[64:67], v[32:47]
	s_waitcnt lgkmcnt(4)
	v_mfma_f32_32x32x16_bf16 v[16:31], v[104:107], v[64:67], v[16:31]
	s_waitcnt lgkmcnt(2)
	v_mfma_f32_32x32x16_bf16 v[32:47], v[108:111], v[68:71], v[32:47]
	s_waitcnt lgkmcnt(0)
	v_mfma_f32_32x32x16_bf16 v[16:31], v[112:115], v[68:71], v[16:31]
	s_setprio 0
	s_andn2_b64 vcc, exec, s[80:81]
	s_mov_b64 s[16:17], -1
	s_cbranch_vccnz .LBB0_996
	s_lshl_b64 s[12:13], 1, s96
	s_andn2_b64 s[12:13], s[86:87], s[12:13]
	s_mov_b64 s[16:17], 0
	s_waitcnt vmcnt(1)
	ds_write_b128 v192, v[148:151]
	s_waitcnt vmcnt(0)
	ds_write_b128 v194, v[152:155] offset:18432
	s_waitcnt lgkmcnt(0)
	s_barrier
	s_branch .LBB0_996
